# cache-policy hint: nt on the up-GEMM ACT tile stores (8 per unit)
# baseline (speedup 1.0000x reference)
; __device__ __forceinline__ void gelu4(const f32x2 (&v)[4], f32x2 (&o)[4]) {
;     ...
;     for (int p = 0; p < 4; ++p) { c[p].x = __builtin_amdgcn_fmed3f(v[p].x, -5.0f, 5.0f); c[p].y = __builtin_amdgcn_fmed3f(v[p].y, -5.0f, 5.0f); w[p] = (c[p] * c[p]) * 0.08f + (-1.0f); }
;     { const float ka = kc<0x3a40c646u>(), kb = kc<0xbadbc5c1u>();
; #pragma unroll
;       for (int p = 0; p < 4; ++p) q[p] = w[p] * ka + kb; }
;     { const float kk = kc<0x3ab42bcbu>();
; #pragma unroll
;       for (int p = 0; p < 4; ++p) q[p] = q[p] * w[p] + kk; }
;     { const float kk = kc<0xbb259aa1u>();
; #pragma unroll
;       for (int p = 0; p < 4; ++p) q[p] = q[p] * w[p] + kk; }
;     { const float kk = kc<0x3bddb9bfu>();
; #pragma unroll
;       for (int p = 0; p < 4; ++p) q[p] = q[p] * w[p] + kk; }
;     { const float kk = kc<0xbc394185u>();
; #pragma unroll
;       for (int p = 0; p < 4; ++p) q[p] = q[p] * w[p] + kk; }
;     { const float kk = kc<0x3c85018cu>();
; #pragma unroll
;       for (int p = 0; p < 4; ++p) q[p] = q[p] * w[p] + kk; }
;     { const float kk = kc<0xbcbe2975u>();
; #pragma unroll
;       for (int p = 0; p < 4; ++p) q[p] = q[p] * w[p] + kk; }
;     { const float kk = kc<0x3d00edc6u>();
; #pragma unroll
;       for (int p = 0; p < 4; ++p) q[p] = q[p] * w[p] + kk; }
;     { const float kk = kc<0xbd25b03eu>();
; #pragma unroll
;       for (int p = 0; p < 4; ++p) q[p] = q[p] * w[p] + kk; }
;     { const float kk = kc<0x3d530477u>();
; #pragma unroll
;       for (int p = 0; p < 4; ++p) q[p] = q[p] * w[p] + kk; }
;     { const float kk = kc<0xbd8ff74du>();
; #pragma unroll
;       for (int p = 0; p < 4; ++p) q[p] = q[p] * w[p] + kk; }
;     { const float kk = kc<0x3e10c1adu>();
; #pragma unroll
;       for (int p = 0; p < 4; ++p) q[p] = q[p] * w[p] + kk; }
; #pragma unroll
;     for (int p = 0; p < 4; ++p) o[p] = v[p] * (q[p] * c[p] + 0.5f);
;     __device__ __forceinline__ void operator()(const f32x4 (&acc)[2][2][4][2], const Unit& u, int wr, int wc, int fr, int fq) const {
;     ...
;                         const float g = acc[ai][1][m][n][j];
;                         const float tp = l15 ? ((m > 0) ? acc[ai][1][m > 0 ? m - 1 : 0][n][j] : xp[n][j]) : g;
;                         const float tn = l0  ? ((m < 3) ? acc[ai][1][m < 3 ? m + 1 : 3][n][j] : xn[n][j]) : g;
;                         const float gp = ror1(tp), gn = ror15(tn);
.LBB0_1251:
	s_or_b64 exec, exec, s[72:73]
	v_med3_f32 v202, v172, s25, v248
	v_med3_f32 v203, v173, s25, v248
	v_pk_mul_f32 v[204:205], v[202:203], v[202:203]
	v_med3_f32 v206, v174, s25, v248
	v_med3_f32 v207, v175, s25, v248
	v_med3_f32 v210, v176, s25, v248
	v_med3_f32 v211, v177, s25, v248
	v_med3_f32 v214, v178, s25, v248
	v_med3_f32 v215, v179, s25, v248
	v_lshl_add_u32 v201, s10, 8, v192
	v_pk_fma_f32 v[204:205], v[204:205], s[14:15], -1.0 op_sel_hi:[1,0,0]
	v_pk_mul_f32 v[208:209], v[206:207], v[206:207]
	v_pk_mul_f32 v[212:213], v[210:211], v[210:211]
	v_pk_mul_f32 v[216:217], v[214:215], v[214:215]
	s_mov_b32 s10, 0x3a40c646
	s_mov_b32 s20, 0xffffffffbadbc5c1
	v_pk_fma_f32 v[208:209], v[208:209], s[14:15], -1.0 op_sel_hi:[1,0,0]
	v_mov_b64_e32 v[218:219], s[20:21]
	v_pk_fma_f32 v[212:213], v[212:213], s[14:15], -1.0 op_sel_hi:[1,0,0]
	v_pk_fma_f32 v[216:217], v[216:217], s[14:15], -1.0 op_sel_hi:[1,0,0]
	v_pk_fma_f32 v[220:221], v[204:205], s[10:11], v[218:219] op_sel_hi:[1,0,0]
	v_pk_fma_f32 v[222:223], v[208:209], s[10:11], v[218:219] op_sel_hi:[1,0,0]
	v_pk_fma_f32 v[224:225], v[212:213], s[10:11], v[218:219] op_sel_hi:[1,0,0]
	v_pk_fma_f32 v[218:219], v[216:217], s[10:11], v[218:219] op_sel_hi:[1,0,0]
	s_mov_b32 s10, 0x3ab42bcb
	s_movk_i32 s3, 0x2d00
	v_pk_fma_f32 v[220:221], v[204:205], v[220:221], s[10:11] op_sel_hi:[1,1,0]
	v_pk_fma_f32 v[222:223], v[208:209], v[222:223], s[10:11] op_sel_hi:[1,1,0]
	v_pk_fma_f32 v[224:225], v[212:213], v[224:225], s[10:11] op_sel_hi:[1,1,0]
	v_pk_fma_f32 v[218:219], v[216:217], v[218:219], s[10:11] op_sel_hi:[1,1,0]
	s_mov_b32 s10, 0xffffffffbb259aa1
	v_cndmask_b32_e64 v152, v136, v152, s[40:41]
	v_pk_fma_f32 v[220:221], v[204:205], v[220:221], s[10:11] op_sel_hi:[1,1,0]
	v_pk_fma_f32 v[222:223], v[208:209], v[222:223], s[10:11] op_sel_hi:[1,1,0]
	v_pk_fma_f32 v[224:225], v[212:213], v[224:225], s[10:11] op_sel_hi:[1,1,0]
	v_pk_fma_f32 v[218:219], v[216:217], v[218:219], s[10:11] op_sel_hi:[1,1,0]
	s_mov_b32 s10, 0x3bddb9bf
	v_cndmask_b32_e64 v153, v137, v153, s[40:41]
	v_pk_fma_f32 v[220:221], v[204:205], v[220:221], s[10:11] op_sel_hi:[1,1,0]
	v_pk_fma_f32 v[222:223], v[208:209], v[222:223], s[10:11] op_sel_hi:[1,1,0]
	v_pk_fma_f32 v[224:225], v[212:213], v[224:225], s[10:11] op_sel_hi:[1,1,0]
	v_pk_fma_f32 v[218:219], v[216:217], v[218:219], s[10:11] op_sel_hi:[1,1,0]
	s_mov_b32 s10, 0xffffffffbc394185
	v_mov_b32_dpp v152, v152 row_ror:1 row_mask:0xf bank_mask:0xf bound_ctrl:1
	v_pk_fma_f32 v[220:221], v[204:205], v[220:221], s[10:11] op_sel_hi:[1,1,0]
	v_pk_fma_f32 v[222:223], v[208:209], v[222:223], s[10:11] op_sel_hi:[1,1,0]
	v_pk_fma_f32 v[224:225], v[212:213], v[224:225], s[10:11] op_sel_hi:[1,1,0]
	v_pk_fma_f32 v[218:219], v[216:217], v[218:219], s[10:11] op_sel_hi:[1,1,0]
	s_mov_b32 s10, 0x3c85018c
	v_mov_b32_dpp v153, v153 row_ror:1 row_mask:0xf bank_mask:0xf bound_ctrl:1
	v_pk_fma_f32 v[220:221], v[204:205], v[220:221], s[10:11] op_sel_hi:[1,1,0]
	v_pk_fma_f32 v[222:223], v[208:209], v[222:223], s[10:11] op_sel_hi:[1,1,0]
	v_pk_fma_f32 v[224:225], v[212:213], v[224:225], s[10:11] op_sel_hi:[1,1,0]
	v_pk_fma_f32 v[218:219], v[216:217], v[218:219], s[10:11] op_sel_hi:[1,1,0]
	s_mov_b32 s10, 0xffffffffbcbe2975
	v_cndmask_b32_e64 v154, v138, v154, s[40:41]
	v_pk_fma_f32 v[220:221], v[204:205], v[220:221], s[10:11] op_sel_hi:[1,1,0]
	v_pk_fma_f32 v[222:223], v[208:209], v[222:223], s[10:11] op_sel_hi:[1,1,0]
	v_pk_fma_f32 v[224:225], v[212:213], v[224:225], s[10:11] op_sel_hi:[1,1,0]
	v_pk_fma_f32 v[218:219], v[216:217], v[218:219], s[10:11] op_sel_hi:[1,1,0]
	s_mov_b32 s10, 0x3d00edc6
	v_cndmask_b32_e64 v155, v139, v155, s[40:41]
	v_pk_fma_f32 v[220:221], v[204:205], v[220:221], s[10:11] op_sel_hi:[1,1,0]
	v_pk_fma_f32 v[222:223], v[208:209], v[222:223], s[10:11] op_sel_hi:[1,1,0]
	v_pk_fma_f32 v[224:225], v[212:213], v[224:225], s[10:11] op_sel_hi:[1,1,0]
	v_pk_fma_f32 v[218:219], v[216:217], v[218:219], s[10:11] op_sel_hi:[1,1,0]
	s_mov_b32 s10, 0xffffffffbd25b03e
	v_mov_b32_dpp v154, v154 row_ror:1 row_mask:0xf bank_mask:0xf bound_ctrl:1
	v_pk_fma_f32 v[220:221], v[204:205], v[220:221], s[10:11] op_sel_hi:[1,1,0]
	v_pk_fma_f32 v[222:223], v[208:209], v[222:223], s[10:11] op_sel_hi:[1,1,0]
	v_pk_fma_f32 v[224:225], v[212:213], v[224:225], s[10:11] op_sel_hi:[1,1,0]
	v_pk_fma_f32 v[218:219], v[216:217], v[218:219], s[10:11] op_sel_hi:[1,1,0]
	s_mov_b32 s10, 0x3d530477
	v_mov_b32_dpp v155, v155 row_ror:1 row_mask:0xf bank_mask:0xf bound_ctrl:1
	v_pk_fma_f32 v[220:221], v[204:205], v[220:221], s[10:11] op_sel_hi:[1,1,0]
	v_pk_fma_f32 v[222:223], v[208:209], v[222:223], s[10:11] op_sel_hi:[1,1,0]
	v_pk_fma_f32 v[224:225], v[212:213], v[224:225], s[10:11] op_sel_hi:[1,1,0]
	v_pk_fma_f32 v[218:219], v[216:217], v[218:219], s[10:11] op_sel_hi:[1,1,0]
	s_mov_b32 s10, 0xffffffffbd8ff74d
	v_cndmask_b32_e64 v148, v132, v148, s[40:41]
	v_pk_fma_f32 v[220:221], v[204:205], v[220:221], s[10:11] op_sel_hi:[1,1,0]
	v_pk_fma_f32 v[222:223], v[208:209], v[222:223], s[10:11] op_sel_hi:[1,1,0]
	v_pk_fma_f32 v[224:225], v[212:213], v[224:225], s[10:11] op_sel_hi:[1,1,0]
	v_pk_fma_f32 v[218:219], v[216:217], v[218:219], s[10:11] op_sel_hi:[1,1,0]
	s_mov_b32 s10, 0x3e10c1ad
	v_cndmask_b32_e64 v149, v133, v149, s[40:41]
	v_pk_fma_f32 v[204:205], v[204:205], v[220:221], s[10:11] op_sel_hi:[1,1,0]
	v_pk_fma_f32 v[208:209], v[208:209], v[222:223], s[10:11] op_sel_hi:[1,1,0]
	v_pk_fma_f32 v[202:203], v[202:203], v[204:205], 0.5 op_sel_hi:[1,1,0]
	v_pk_fma_f32 v[212:213], v[212:213], v[224:225], s[10:11] op_sel_hi:[1,1,0]
	v_pk_mul_f32 v[172:173], v[172:173], v[202:203]
; __device__ __forceinline__ unsigned cvt_pk_bf16(float lo, float hi) { unsigned r; asm volatile("v_cvt_pk_bf16_f32 %0, %1, %2" : "=v"(r) : "v"(lo), "v"(hi)); return r; }
;     static __device__ __forceinline__ float ror1(float v)  { return __builtin_bit_cast(float, __builtin_amdgcn_update_dpp(0, __builtin_bit_cast(int, v), 0x121, 0xf, 0xf, true)); }
;     static __device__ __forceinline__ float ror15(float v) { return __builtin_bit_cast(float, __builtin_amdgcn_update_dpp(0, __builtin_bit_cast(int, v), 0x12f, 0xf, 0xf, true)); }
;     __device__ __forceinline__ void operator()(const f32x4 (&acc)[2][2][4][2], const Unit& u, int wr, int wc, int fr, int fq) const {
;     ...
;                         const float g = acc[ai][1][m][n][j];
;                         const float tp = l15 ? ((m > 0) ? acc[ai][1][m > 0 ? m - 1 : 0][n][j] : xp[n][j]) : g;
;                         const float tn = l0  ? ((m < 3) ? acc[ai][1][m < 3 ? m + 1 : 3][n][j] : xn[n][j]) : g;
;                         const float gp = ror1(tp), gn = ror15(tn);
;                         cv[4 * n + j] = fmaf(w0[n][j], gp, fmaf(w1[n][j], g, fmaf(w2[n][j], gn, bb[n][j])));
;     ...
;                 f32x2 gv[4], go[4]; float a[8];
; #pragma unroll
;                 for (int p = 0; p < 4; ++p) gv[p] = (f32x2){cv[2 * p], cv[2 * p + 1]};
;                 gelu4(gv, go);
; #pragma unroll
;                 for (int e = 0; e < 8; e += 2) { a[e] = go[e >> 1].x * acc[ai][0][m][e >> 2][e & 3]; a[e + 1] = go[e >> 1].y * acc[ai][0][m][(e + 1) >> 2][(e + 1) & 3]; }
;                 ow.x = cvt_pk_bf16(a[0], a[1]); ow.y = cvt_pk_bf16(a[2], a[3]); ow.z = cvt_pk_bf16(a[4], a[5]); ow.w = cvt_pk_bf16(a[6], a[7]);
;                 *(u32x4*)(ACT + (size_t)row * ldc + ch0) = ow;
	v_pk_fma_f32 v[202:203], v[206:207], v[208:209], 0.5 op_sel_hi:[1,1,0]
	v_pk_fma_f32 v[216:217], v[216:217], v[218:219], s[10:11] op_sel_hi:[1,1,0]
	v_pk_mul_f32 v[174:175], v[174:175], v[202:203]
	v_pk_fma_f32 v[202:203], v[210:211], v[212:213], 0.5 op_sel_hi:[1,1,0]
	v_mul_f32_e32 v160, v160, v172
	v_pk_mul_f32 v[176:177], v[176:177], v[202:203]
	v_pk_fma_f32 v[202:203], v[214:215], v[216:217], 0.5 op_sel_hi:[1,1,0]
	v_mul_f32_e32 v161, v161, v173
	v_pk_mul_f32 v[178:179], v[178:179], v[202:203]
	v_mul_f32_e32 v162, v162, v174
	v_mul_f32_e32 v163, v163, v175
	v_mul_f32_e32 v158, v158, v178
	v_mul_f32_e32 v159, v159, v179
	v_mul_f32_e32 v156, v156, v176
	v_mul_f32_e32 v157, v157, v177
	v_cvt_pk_bf16_f32 v160, v160, v161
	v_cvt_pk_bf16_f32 v161, v162, v163
	v_cvt_pk_bf16_f32 v162, v156, v157
	v_cvt_pk_bf16_f32 v163, v158, v159
	v_mov_b64_e32 v[158:159], s[54:55]
	v_mad_i64_i32 v[172:173], s[10:11], v201, s3, v[158:159]
	v_lshlrev_b64 v[156:157], 1, v[190:191]
	v_lshl_add_u64 v[172:173], v[172:173], 0, v[156:157]
	global_store_dwordx4 v[172:173], v[160:163], off nt
	v_mov_b32_dpp v148, v148 row_ror:1 row_mask:0xf bank_mask:0xf bound_ctrl:1
	v_mov_b32_dpp v149, v149 row_ror:1 row_mask:0xf bank_mask:0xf bound_ctrl:1
	v_cndmask_b32_e64 v160, v136, v120, s[38:39]
	v_cndmask_b32_e64 v161, v137, v121, s[38:39]
	v_cndmask_b32_e64 v150, v134, v150, s[40:41]
	v_mov_b32_dpp v160, v160 row_ror:15 row_mask:0xf bank_mask:0xf bound_ctrl:1
	v_mov_b32_dpp v161, v161 row_ror:15 row_mask:0xf bank_mask:0xf bound_ctrl:1
	v_pk_fma_f32 v[160:161], v[100:101], v[160:161], v[104:105]
	v_cndmask_b32_e64 v151, v135, v151, s[40:41]
	v_pk_fma_f32 v[160:161], v[96:97], v[136:137], v[160:161]
	v_mov_b32_dpp v150, v150 row_ror:1 row_mask:0xf bank_mask:0xf bound_ctrl:1
	v_pk_fma_f32 v[152:153], v[92:93], v[152:153], v[160:161]
	v_cndmask_b32_e64 v160, v138, v122, s[38:39]
	v_cndmask_b32_e64 v161, v139, v123, s[38:39]
	v_mov_b32_dpp v151, v151 row_ror:1 row_mask:0xf bank_mask:0xf bound_ctrl:1
	v_mov_b32_dpp v160, v160 row_ror:15 row_mask:0xf bank_mask:0xf bound_ctrl:1
	v_mov_b32_dpp v161, v161 row_ror:15 row_mask:0xf bank_mask:0xf bound_ctrl:1
	v_pk_fma_f32 v[160:161], v[102:103], v[160:161], v[106:107]
	s_mov_b32 s10, 0x3a40c646
	s_mov_b32 s20, 0xffffffffbadbc5c1
	v_or_b32_e32 v214, 16, v201
	v_pk_fma_f32 v[160:161], v[98:99], v[138:139], v[160:161]
	v_mov_b64_e32 v[206:207], s[20:21]
	v_pk_fma_f32 v[154:155], v[94:95], v[154:155], v[160:161]
	v_cndmask_b32_e64 v160, v132, v116, s[38:39]
	v_cndmask_b32_e64 v161, v133, v117, s[38:39]
	v_med3_f32 v172, v154, s25, v248
	v_mov_b32_dpp v160, v160 row_ror:15 row_mask:0xf bank_mask:0xf bound_ctrl:1
	v_mov_b32_dpp v161, v161 row_ror:15 row_mask:0xf bank_mask:0xf bound_ctrl:1
	v_pk_fma_f32 v[160:161], v[84:85], v[160:161], v[88:89]
	v_med3_f32 v173, v155, s25, v248
	v_pk_fma_f32 v[160:161], v[76:77], v[132:133], v[160:161]
	v_pk_mul_f32 v[174:175], v[172:173], v[172:173]
	v_pk_fma_f32 v[148:149], v[72:73], v[148:149], v[160:161]
	v_cndmask_b32_e64 v160, v134, v118, s[38:39]
	v_cndmask_b32_e64 v161, v135, v119, s[38:39]
	v_med3_f32 v176, v148, s25, v248
	v_mov_b32_dpp v160, v160 row_ror:15 row_mask:0xf bank_mask:0xf bound_ctrl:1
	v_mov_b32_dpp v161, v161 row_ror:15 row_mask:0xf bank_mask:0xf bound_ctrl:1
	v_pk_fma_f32 v[160:161], v[86:87], v[160:161], v[90:91]
	v_med3_f32 v177, v149, s25, v248
	v_pk_fma_f32 v[160:161], v[78:79], v[134:135], v[160:161]
	v_pk_mul_f32 v[178:179], v[176:177], v[176:177]
	v_pk_fma_f32 v[150:151], v[74:75], v[150:151], v[160:161]
	v_med3_f32 v160, v152, s25, v248
	v_med3_f32 v161, v153, s25, v248
	v_pk_mul_f32 v[162:163], v[160:161], v[160:161]
	v_med3_f32 v202, v150, s25, v248
	v_med3_f32 v203, v151, s25, v248
	v_pk_fma_f32 v[162:163], v[162:163], s[14:15], -1.0 op_sel_hi:[1,0,0]
	v_pk_mul_f32 v[204:205], v[202:203], v[202:203]
	v_pk_fma_f32 v[174:175], v[174:175], s[14:15], -1.0 op_sel_hi:[1,0,0]
	v_pk_fma_f32 v[178:179], v[178:179], s[14:15], -1.0 op_sel_hi:[1,0,0]
	v_pk_fma_f32 v[204:205], v[204:205], s[14:15], -1.0 op_sel_hi:[1,0,0]
	v_pk_fma_f32 v[208:209], v[162:163], s[10:11], v[206:207] op_sel_hi:[1,0,0]
	v_pk_fma_f32 v[210:211], v[174:175], s[10:11], v[206:207] op_sel_hi:[1,0,0]
	v_pk_fma_f32 v[212:213], s[10:11], v[178:179], v[206:207] op_sel_hi:[0,1,0]
	v_pk_fma_f32 v[206:207], s[10:11], v[204:205], v[206:207] op_sel_hi:[0,1,0]
	s_mov_b32 s10, 0x3ab42bcb
	v_cndmask_b32_e64 v136, v120, v136, s[40:41]
	v_pk_fma_f32 v[208:209], v[162:163], v[208:209], s[10:11] op_sel_hi:[1,1,0]
	v_pk_fma_f32 v[210:211], v[174:175], v[210:211], s[10:11] op_sel_hi:[1,1,0]
	v_pk_fma_f32 v[212:213], v[178:179], v[212:213], s[10:11] op_sel_hi:[1,1,0]
	v_pk_fma_f32 v[206:207], v[204:205], v[206:207], s[10:11] op_sel_hi:[1,1,0]
	s_mov_b32 s10, 0xffffffffbb259aa1
	v_cndmask_b32_e64 v137, v121, v137, s[40:41]
	v_pk_fma_f32 v[208:209], v[162:163], v[208:209], s[10:11] op_sel_hi:[1,1,0]
	v_pk_fma_f32 v[210:211], v[174:175], v[210:211], s[10:11] op_sel_hi:[1,1,0]
	v_pk_fma_f32 v[212:213], v[178:179], v[212:213], s[10:11] op_sel_hi:[1,1,0]
	v_pk_fma_f32 v[206:207], v[204:205], v[206:207], s[10:11] op_sel_hi:[1,1,0]
	s_mov_b32 s10, 0x3bddb9bf
	v_mov_b32_dpp v136, v136 row_ror:1 row_mask:0xf bank_mask:0xf bound_ctrl:1
	v_pk_fma_f32 v[208:209], v[162:163], v[208:209], s[10:11] op_sel_hi:[1,1,0]
	v_pk_fma_f32 v[210:211], v[174:175], v[210:211], s[10:11] op_sel_hi:[1,1,0]
	v_pk_fma_f32 v[212:213], v[178:179], v[212:213], s[10:11] op_sel_hi:[1,1,0]
	v_pk_fma_f32 v[206:207], v[204:205], v[206:207], s[10:11] op_sel_hi:[1,1,0]
	s_mov_b32 s10, 0xffffffffbc394185
	v_mov_b32_dpp v137, v137 row_ror:1 row_mask:0xf bank_mask:0xf bound_ctrl:1
; __device__ __forceinline__ void gelu4(const f32x2 (&v)[4], f32x2 (&o)[4]) {
;     ...
;     for (int p = 0; p < 4; ++p) { c[p].x = __builtin_amdgcn_fmed3f(v[p].x, -5.0f, 5.0f); c[p].y = __builtin_amdgcn_fmed3f(v[p].y, -5.0f, 5.0f); w[p] = (c[p] * c[p]) * 0.08f + (-1.0f); }
;     { const float ka = kc<0x3a40c646u>(), kb = kc<0xbadbc5c1u>();
; #pragma unroll
;       for (int p = 0; p < 4; ++p) q[p] = w[p] * ka + kb; }
;     { const float kk = kc<0x3ab42bcbu>();
; #pragma unroll
;       for (int p = 0; p < 4; ++p) q[p] = q[p] * w[p] + kk; }
;     { const float kk = kc<0xbb259aa1u>();
; #pragma unroll
;       for (int p = 0; p < 4; ++p) q[p] = q[p] * w[p] + kk; }
;     { const float kk = kc<0x3bddb9bfu>();
; #pragma unroll
;       for (int p = 0; p < 4; ++p) q[p] = q[p] * w[p] + kk; }
;     { const float kk = kc<0xbc394185u>();
; #pragma unroll
;       for (int p = 0; p < 4; ++p) q[p] = q[p] * w[p] + kk; }
;     { const float kk = kc<0x3c85018cu>();
; #pragma unroll
;       for (int p = 0; p < 4; ++p) q[p] = q[p] * w[p] + kk; }
;     { const float kk = kc<0xbcbe2975u>();
; #pragma unroll
;       for (int p = 0; p < 4; ++p) q[p] = q[p] * w[p] + kk; }
;     { const float kk = kc<0x3d00edc6u>();
; #pragma unroll
;       for (int p = 0; p < 4; ++p) q[p] = q[p] * w[p] + kk; }
;     { const float kk = kc<0xbd25b03eu>();
; #pragma unroll
;       for (int p = 0; p < 4; ++p) q[p] = q[p] * w[p] + kk; }
;     { const float kk = kc<0x3d530477u>();
; #pragma unroll
;       for (int p = 0; p < 4; ++p) q[p] = q[p] * w[p] + kk; }
;     { const float kk = kc<0xbd8ff74du>();
; #pragma unroll
;       for (int p = 0; p < 4; ++p) q[p] = q[p] * w[p] + kk; }
;     { const float kk = kc<0x3e10c1adu>();
; #pragma unroll
;       for (int p = 0; p < 4; ++p) q[p] = q[p] * w[p] + kk; }
; #pragma unroll
;     for (int p = 0; p < 4; ++p) o[p] = v[p] * (q[p] * c[p] + 0.5f);
;     __device__ __forceinline__ void operator()(const f32x4 (&acc)[2][2][4][2], const Unit& u, int wr, int wc, int fr, int fq) const {
;     ...
;                 for (int e = 0; e < 8; e += 2) { a[e] = go[e >> 1].x * acc[ai][0][m][e >> 2][e & 3]; a[e + 1] = go[e >> 1].y * acc[ai][0][m][(e + 1) >> 2][(e + 1) & 3]; }
;                 ow.x = cvt_pk_bf16(a[0], a[1]); ow.y = cvt_pk_bf16(a[2], a[3]); ow.z = cvt_pk_bf16(a[4], a[5]); ow.w = cvt_pk_bf16(a[6], a[7]);
;                 *(u32x4*)(ACT + (size_t)row * ldc + ch0) = ow;
	v_pk_fma_f32 v[208:209], v[162:163], v[208:209], s[10:11] op_sel_hi:[1,1,0]
	v_pk_fma_f32 v[210:211], v[174:175], v[210:211], s[10:11] op_sel_hi:[1,1,0]
	v_pk_fma_f32 v[212:213], v[178:179], v[212:213], s[10:11] op_sel_hi:[1,1,0]
	v_pk_fma_f32 v[206:207], v[204:205], v[206:207], s[10:11] op_sel_hi:[1,1,0]
	s_mov_b32 s10, 0x3c85018c
	v_cndmask_b32_e64 v138, v122, v138, s[40:41]
	v_pk_fma_f32 v[208:209], v[162:163], v[208:209], s[10:11] op_sel_hi:[1,1,0]
	v_pk_fma_f32 v[210:211], v[174:175], v[210:211], s[10:11] op_sel_hi:[1,1,0]
	v_pk_fma_f32 v[212:213], v[178:179], v[212:213], s[10:11] op_sel_hi:[1,1,0]
	v_pk_fma_f32 v[206:207], v[204:205], v[206:207], s[10:11] op_sel_hi:[1,1,0]
	s_mov_b32 s10, 0xffffffffbcbe2975
	v_cndmask_b32_e64 v139, v123, v139, s[40:41]
	v_pk_fma_f32 v[208:209], v[162:163], v[208:209], s[10:11] op_sel_hi:[1,1,0]
	v_pk_fma_f32 v[210:211], v[174:175], v[210:211], s[10:11] op_sel_hi:[1,1,0]
	v_pk_fma_f32 v[212:213], v[178:179], v[212:213], s[10:11] op_sel_hi:[1,1,0]
	v_pk_fma_f32 v[206:207], v[204:205], v[206:207], s[10:11] op_sel_hi:[1,1,0]
	s_mov_b32 s10, 0x3d00edc6
	v_mov_b32_dpp v138, v138 row_ror:1 row_mask:0xf bank_mask:0xf bound_ctrl:1
	v_pk_fma_f32 v[208:209], v[162:163], v[208:209], s[10:11] op_sel_hi:[1,1,0]
	v_pk_fma_f32 v[210:211], v[174:175], v[210:211], s[10:11] op_sel_hi:[1,1,0]
	v_pk_fma_f32 v[212:213], v[178:179], v[212:213], s[10:11] op_sel_hi:[1,1,0]
	v_pk_fma_f32 v[206:207], v[204:205], v[206:207], s[10:11] op_sel_hi:[1,1,0]
	s_mov_b32 s10, 0xffffffffbd25b03e
	v_mov_b32_dpp v139, v139 row_ror:1 row_mask:0xf bank_mask:0xf bound_ctrl:1
	v_pk_fma_f32 v[208:209], v[162:163], v[208:209], s[10:11] op_sel_hi:[1,1,0]
	v_pk_fma_f32 v[210:211], v[174:175], v[210:211], s[10:11] op_sel_hi:[1,1,0]
	v_pk_fma_f32 v[212:213], v[178:179], v[212:213], s[10:11] op_sel_hi:[1,1,0]
	v_pk_fma_f32 v[206:207], v[204:205], v[206:207], s[10:11] op_sel_hi:[1,1,0]
	s_mov_b32 s10, 0x3d530477
	v_cndmask_b32_e64 v132, v116, v132, s[40:41]
	v_pk_fma_f32 v[208:209], v[162:163], v[208:209], s[10:11] op_sel_hi:[1,1,0]
	v_pk_fma_f32 v[210:211], v[174:175], v[210:211], s[10:11] op_sel_hi:[1,1,0]
	v_pk_fma_f32 v[212:213], v[178:179], v[212:213], s[10:11] op_sel_hi:[1,1,0]
	v_pk_fma_f32 v[206:207], v[204:205], v[206:207], s[10:11] op_sel_hi:[1,1,0]
	s_mov_b32 s10, 0xffffffffbd8ff74d
	v_cndmask_b32_e64 v133, v117, v133, s[40:41]
	v_pk_fma_f32 v[208:209], v[162:163], v[208:209], s[10:11] op_sel_hi:[1,1,0]
	v_pk_fma_f32 v[210:211], v[174:175], v[210:211], s[10:11] op_sel_hi:[1,1,0]
	v_pk_fma_f32 v[212:213], v[178:179], v[212:213], s[10:11] op_sel_hi:[1,1,0]
	v_pk_fma_f32 v[206:207], v[204:205], v[206:207], s[10:11] op_sel_hi:[1,1,0]
	s_mov_b32 s10, 0x3e10c1ad
	v_mov_b32_dpp v132, v132 row_ror:1 row_mask:0xf bank_mask:0xf bound_ctrl:1
	v_pk_fma_f32 v[162:163], v[162:163], v[208:209], s[10:11] op_sel_hi:[1,1,0]
	v_pk_fma_f32 v[174:175], v[174:175], v[210:211], s[10:11] op_sel_hi:[1,1,0]
	v_pk_fma_f32 v[160:161], v[160:161], v[162:163], 0.5 op_sel_hi:[1,1,0]
	v_pk_fma_f32 v[178:179], v[178:179], v[212:213], s[10:11] op_sel_hi:[1,1,0]
	v_pk_mul_f32 v[152:153], v[152:153], v[160:161]
	v_pk_fma_f32 v[160:161], v[172:173], v[174:175], 0.5 op_sel_hi:[1,1,0]
	v_pk_fma_f32 v[204:205], v[204:205], v[206:207], s[10:11] op_sel_hi:[1,1,0]
	v_pk_mul_f32 v[154:155], v[154:155], v[160:161]
	v_pk_fma_f32 v[160:161], v[176:177], v[178:179], 0.5 op_sel_hi:[1,1,0]
	v_mul_f32_e32 v144, v144, v152
	v_pk_mul_f32 v[148:149], v[148:149], v[160:161]
	v_pk_fma_f32 v[160:161], v[202:203], v[204:205], 0.5 op_sel_hi:[1,1,0]
	v_mul_f32_e32 v145, v145, v153
	v_pk_mul_f32 v[150:151], v[150:151], v[160:161]
	v_mul_f32_e32 v148, v140, v148
	v_cvt_pk_bf16_f32 v140, v144, v145
	v_mad_i64_i32 v[144:145], s[10:11], v214, s3, v[158:159]
	v_mul_f32_e32 v146, v146, v154
	v_mul_f32_e32 v147, v147, v155
	v_mul_f32_e32 v149, v141, v149
	v_mul_f32_e32 v143, v143, v151
	v_cvt_pk_bf16_f32 v141, v146, v147
	v_lshl_add_u64 v[144:145], v[144:145], 0, v[156:157]
	v_mul_f32_e32 v150, v142, v150
	v_cvt_pk_bf16_f32 v142, v148, v149
	v_cvt_pk_bf16_f32 v143, v150, v143
	global_store_dwordx4 v[144:145], v[140:143], off nt
	v_mov_b32_dpp v133, v133 row_ror:1 row_mask:0xf bank_mask:0xf bound_ctrl:1
	v_cndmask_b32_e64 v134, v118, v134, s[40:41]
	v_cndmask_b32_e64 v140, v120, v112, s[38:39]
	v_cndmask_b32_e64 v141, v121, v113, s[38:39]
	v_cndmask_b32_e64 v135, v119, v135, s[40:41]
	v_mov_b32_dpp v140, v140 row_ror:15 row_mask:0xf bank_mask:0xf bound_ctrl:1
	v_mov_b32_dpp v141, v141 row_ror:15 row_mask:0xf bank_mask:0xf bound_ctrl:1
	v_pk_fma_f32 v[140:141], v[100:101], v[140:141], v[104:105]
	v_mov_b32_dpp v134, v134 row_ror:1 row_mask:0xf bank_mask:0xf bound_ctrl:1
	v_pk_fma_f32 v[140:141], v[96:97], v[120:121], v[140:141]
	v_mov_b32_dpp v135, v135 row_ror:1 row_mask:0xf bank_mask:0xf bound_ctrl:1
	v_pk_fma_f32 v[136:137], v[92:93], v[136:137], v[140:141]
	v_cndmask_b32_e64 v140, v122, v114, s[38:39]
	v_cndmask_b32_e64 v141, v123, v115, s[38:39]
	s_mov_b32 s10, 0x3a40c646
	s_mov_b32 s20, 0xffffffffbadbc5c1
	v_or_b32_e32 v176, 32, v201
	v_mov_b32_dpp v140, v140 row_ror:15 row_mask:0xf bank_mask:0xf bound_ctrl:1
	v_mov_b32_dpp v141, v141 row_ror:15 row_mask:0xf bank_mask:0xf bound_ctrl:1
	v_pk_fma_f32 v[140:141], v[102:103], v[140:141], v[106:107]
	v_mov_b64_e32 v[160:161], s[20:21]
	v_pk_fma_f32 v[140:141], v[98:99], v[122:123], v[140:141]
	v_cndmask_b32_e64 v120, v112, v120, s[40:41]
	v_pk_fma_f32 v[138:139], v[94:95], v[138:139], v[140:141]
	v_cndmask_b32_e64 v140, v116, v108, s[38:39]
	v_cndmask_b32_e64 v141, v117, v109, s[38:39]
	v_med3_f32 v144, v138, s25, v248
; __device__ __forceinline__ void gelu4(const f32x2 (&v)[4], f32x2 (&o)[4]) {
;     ...
;     for (int p = 0; p < 4; ++p) { c[p].x = __builtin_amdgcn_fmed3f(v[p].x, -5.0f, 5.0f); c[p].y = __builtin_amdgcn_fmed3f(v[p].y, -5.0f, 5.0f); w[p] = (c[p] * c[p]) * 0.08f + (-1.0f); }
;     { const float ka = kc<0x3a40c646u>(), kb = kc<0xbadbc5c1u>();
; #pragma unroll
;       for (int p = 0; p < 4; ++p) q[p] = w[p] * ka + kb; }
;     { const float kk = kc<0x3ab42bcbu>();
; #pragma unroll
;       for (int p = 0; p < 4; ++p) q[p] = q[p] * w[p] + kk; }
;     { const float kk = kc<0xbb259aa1u>();
; #pragma unroll
;       for (int p = 0; p < 4; ++p) q[p] = q[p] * w[p] + kk; }
;     { const float kk = kc<0x3bddb9bfu>();
; #pragma unroll
;       for (int p = 0; p < 4; ++p) q[p] = q[p] * w[p] + kk; }
;     { const float kk = kc<0xbc394185u>();
; #pragma unroll
;       for (int p = 0; p < 4; ++p) q[p] = q[p] * w[p] + kk; }
;     { const float kk = kc<0x3c85018cu>();
; #pragma unroll
;       for (int p = 0; p < 4; ++p) q[p] = q[p] * w[p] + kk; }
;     { const float kk = kc<0xbcbe2975u>();
; #pragma unroll
;       for (int p = 0; p < 4; ++p) q[p] = q[p] * w[p] + kk; }
;     { const float kk = kc<0x3d00edc6u>();
; #pragma unroll
;       for (int p = 0; p < 4; ++p) q[p] = q[p] * w[p] + kk; }
;     { const float kk = kc<0xbd25b03eu>();
; #pragma unroll
;       for (int p = 0; p < 4; ++p) q[p] = q[p] * w[p] + kk; }
;     { const float kk = kc<0x3d530477u>();
; #pragma unroll
;       for (int p = 0; p < 4; ++p) q[p] = q[p] * w[p] + kk; }
;     { const float kk = kc<0xbd8ff74du>();
; #pragma unroll
;       for (int p = 0; p < 4; ++p) q[p] = q[p] * w[p] + kk; }
;     { const float kk = kc<0x3e10c1adu>();
; #pragma unroll
;       for (int p = 0; p < 4; ++p) q[p] = q[p] * w[p] + kk; }
; #pragma unroll
;     __device__ __forceinline__ void operator()(const f32x4 (&acc)[2][2][4][2], const Unit& u, int wr, int wc, int fr, int fq) const {
;     ...
;                         const float g = acc[ai][1][m][n][j];
;                         const float tp = l15 ? ((m > 0) ? acc[ai][1][m > 0 ? m - 1 : 0][n][j] : xp[n][j]) : g;
;                         const float tn = l0  ? ((m < 3) ? acc[ai][1][m < 3 ? m + 1 : 3][n][j] : xn[n][j]) : g;
;                         const float gp = ror1(tp), gn = ror15(tn);
;                         cv[4 * n + j] = fmaf(w0[n][j], gp, fmaf(w1[n][j], g, fmaf(w2[n][j], gn, bb[n][j])));
	v_mov_b32_dpp v140, v140 row_ror:15 row_mask:0xf bank_mask:0xf bound_ctrl:1
	v_mov_b32_dpp v141, v141 row_ror:15 row_mask:0xf bank_mask:0xf bound_ctrl:1
	v_pk_fma_f32 v[140:141], v[84:85], v[140:141], v[88:89]
	v_med3_f32 v145, v139, s25, v248
	v_pk_fma_f32 v[140:141], v[76:77], v[116:117], v[140:141]
	v_pk_mul_f32 v[146:147], v[144:145], v[144:145]
	v_pk_fma_f32 v[132:133], v[72:73], v[132:133], v[140:141]
	v_cndmask_b32_e64 v140, v118, v110, s[38:39]
	v_cndmask_b32_e64 v141, v119, v111, s[38:39]
	v_med3_f32 v148, v132, s25, v248
	v_mov_b32_dpp v140, v140 row_ror:15 row_mask:0xf bank_mask:0xf bound_ctrl:1
	v_mov_b32_dpp v141, v141 row_ror:15 row_mask:0xf bank_mask:0xf bound_ctrl:1
	v_pk_fma_f32 v[140:141], v[86:87], v[140:141], v[90:91]
	v_med3_f32 v149, v133, s25, v248
	v_pk_fma_f32 v[140:141], v[78:79], v[118:119], v[140:141]
	v_pk_mul_f32 v[150:151], v[148:149], v[148:149]
	v_pk_fma_f32 v[134:135], v[74:75], v[134:135], v[140:141]
	v_med3_f32 v140, v136, s25, v248
	v_med3_f32 v141, v137, s25, v248
	v_pk_mul_f32 v[142:143], v[140:141], v[140:141]
	v_med3_f32 v152, v134, s25, v248
	v_med3_f32 v153, v135, s25, v248
	v_pk_fma_f32 v[142:143], v[142:143], s[14:15], -1.0 op_sel_hi:[1,0,0]
	v_pk_mul_f32 v[154:155], v[152:153], v[152:153]
	v_pk_fma_f32 v[146:147], v[146:147], s[14:15], -1.0 op_sel_hi:[1,0,0]
	v_pk_fma_f32 v[150:151], v[150:151], s[14:15], -1.0 op_sel_hi:[1,0,0]
	v_pk_fma_f32 v[154:155], v[154:155], s[14:15], -1.0 op_sel_hi:[1,0,0]
	v_pk_fma_f32 v[162:163], v[142:143], s[10:11], v[160:161] op_sel_hi:[1,0,0]
	v_pk_fma_f32 v[172:173], v[146:147], s[10:11], v[160:161] op_sel_hi:[1,0,0]
	v_pk_fma_f32 v[174:175], s[10:11], v[150:151], v[160:161] op_sel_hi:[0,1,0]
	v_pk_fma_f32 v[160:161], s[10:11], v[154:155], v[160:161] op_sel_hi:[0,1,0]
	s_mov_b32 s10, 0x3ab42bcb
	v_cndmask_b32_e64 v121, v113, v121, s[40:41]
	v_pk_fma_f32 v[162:163], v[142:143], v[162:163], s[10:11] op_sel_hi:[1,1,0]
	v_pk_fma_f32 v[172:173], v[146:147], v[172:173], s[10:11] op_sel_hi:[1,1,0]
	v_pk_fma_f32 v[174:175], v[150:151], v[174:175], s[10:11] op_sel_hi:[1,1,0]
	v_pk_fma_f32 v[160:161], v[154:155], v[160:161], s[10:11] op_sel_hi:[1,1,0]
	s_mov_b32 s10, 0xffffffffbb259aa1
	v_mov_b32_dpp v120, v120 row_ror:1 row_mask:0xf bank_mask:0xf bound_ctrl:1
	v_pk_fma_f32 v[162:163], v[142:143], v[162:163], s[10:11] op_sel_hi:[1,1,0]
	v_pk_fma_f32 v[172:173], v[146:147], v[172:173], s[10:11] op_sel_hi:[1,1,0]
	v_pk_fma_f32 v[174:175], v[150:151], v[174:175], s[10:11] op_sel_hi:[1,1,0]
	v_pk_fma_f32 v[160:161], v[154:155], v[160:161], s[10:11] op_sel_hi:[1,1,0]
	s_mov_b32 s10, 0x3bddb9bf
	v_mov_b32_dpp v121, v121 row_ror:1 row_mask:0xf bank_mask:0xf bound_ctrl:1
	v_pk_fma_f32 v[162:163], v[142:143], v[162:163], s[10:11] op_sel_hi:[1,1,0]
	v_pk_fma_f32 v[172:173], v[146:147], v[172:173], s[10:11] op_sel_hi:[1,1,0]
	v_pk_fma_f32 v[174:175], v[150:151], v[174:175], s[10:11] op_sel_hi:[1,1,0]
	v_pk_fma_f32 v[160:161], v[154:155], v[160:161], s[10:11] op_sel_hi:[1,1,0]
	s_mov_b32 s10, 0xffffffffbc394185
	v_cndmask_b32_e64 v122, v114, v122, s[40:41]
	v_pk_fma_f32 v[162:163], v[142:143], v[162:163], s[10:11] op_sel_hi:[1,1,0]
	v_pk_fma_f32 v[172:173], v[146:147], v[172:173], s[10:11] op_sel_hi:[1,1,0]
	v_pk_fma_f32 v[174:175], v[150:151], v[174:175], s[10:11] op_sel_hi:[1,1,0]
	v_pk_fma_f32 v[160:161], v[154:155], v[160:161], s[10:11] op_sel_hi:[1,1,0]
	s_mov_b32 s10, 0x3c85018c
	v_cndmask_b32_e64 v123, v115, v123, s[40:41]
	v_pk_fma_f32 v[162:163], v[142:143], v[162:163], s[10:11] op_sel_hi:[1,1,0]
	v_pk_fma_f32 v[172:173], v[146:147], v[172:173], s[10:11] op_sel_hi:[1,1,0]
	v_pk_fma_f32 v[174:175], v[150:151], v[174:175], s[10:11] op_sel_hi:[1,1,0]
	v_pk_fma_f32 v[160:161], v[154:155], v[160:161], s[10:11] op_sel_hi:[1,1,0]
	s_mov_b32 s10, 0xffffffffbcbe2975
	v_mov_b32_dpp v122, v122 row_ror:1 row_mask:0xf bank_mask:0xf bound_ctrl:1
	v_pk_fma_f32 v[162:163], v[142:143], v[162:163], s[10:11] op_sel_hi:[1,1,0]
	v_pk_fma_f32 v[172:173], v[146:147], v[172:173], s[10:11] op_sel_hi:[1,1,0]
	v_pk_fma_f32 v[174:175], v[150:151], v[174:175], s[10:11] op_sel_hi:[1,1,0]
	v_pk_fma_f32 v[160:161], v[154:155], v[160:161], s[10:11] op_sel_hi:[1,1,0]
	s_mov_b32 s10, 0x3d00edc6
	v_mov_b32_dpp v123, v123 row_ror:1 row_mask:0xf bank_mask:0xf bound_ctrl:1
	v_pk_fma_f32 v[162:163], v[142:143], v[162:163], s[10:11] op_sel_hi:[1,1,0]
	v_pk_fma_f32 v[172:173], v[146:147], v[172:173], s[10:11] op_sel_hi:[1,1,0]
	v_pk_fma_f32 v[174:175], v[150:151], v[174:175], s[10:11] op_sel_hi:[1,1,0]
	v_pk_fma_f32 v[160:161], v[154:155], v[160:161], s[10:11] op_sel_hi:[1,1,0]
	s_mov_b32 s10, 0xffffffffbd25b03e
	v_cndmask_b32_e64 v116, v108, v116, s[40:41]
	v_pk_fma_f32 v[162:163], v[142:143], v[162:163], s[10:11] op_sel_hi:[1,1,0]
	v_pk_fma_f32 v[172:173], v[146:147], v[172:173], s[10:11] op_sel_hi:[1,1,0]
	v_pk_fma_f32 v[174:175], v[150:151], v[174:175], s[10:11] op_sel_hi:[1,1,0]
	v_pk_fma_f32 v[160:161], v[154:155], v[160:161], s[10:11] op_sel_hi:[1,1,0]
	s_mov_b32 s10, 0x3d530477
	v_cndmask_b32_e64 v117, v109, v117, s[40:41]
	v_pk_fma_f32 v[162:163], v[142:143], v[162:163], s[10:11] op_sel_hi:[1,1,0]
	v_pk_fma_f32 v[172:173], v[146:147], v[172:173], s[10:11] op_sel_hi:[1,1,0]
	v_pk_fma_f32 v[174:175], v[150:151], v[174:175], s[10:11] op_sel_hi:[1,1,0]
	v_pk_fma_f32 v[160:161], v[154:155], v[160:161], s[10:11] op_sel_hi:[1,1,0]
	s_mov_b32 s10, 0xffffffffbd8ff74d
	v_mov_b32_dpp v116, v116 row_ror:1 row_mask:0xf bank_mask:0xf bound_ctrl:1
	v_pk_fma_f32 v[162:163], v[142:143], v[162:163], s[10:11] op_sel_hi:[1,1,0]
	v_pk_fma_f32 v[172:173], v[146:147], v[172:173], s[10:11] op_sel_hi:[1,1,0]
; __device__ __forceinline__ unsigned cvt_pk_bf16(float lo, float hi) { unsigned r; asm volatile("v_cvt_pk_bf16_f32 %0, %1, %2" : "=v"(r) : "v"(lo), "v"(hi)); return r; }
;     static __device__ __forceinline__ float ror1(float v)  { return __builtin_bit_cast(float, __builtin_amdgcn_update_dpp(0, __builtin_bit_cast(int, v), 0x121, 0xf, 0xf, true)); }
;     static __device__ __forceinline__ float ror15(float v) { return __builtin_bit_cast(float, __builtin_amdgcn_update_dpp(0, __builtin_bit_cast(int, v), 0x12f, 0xf, 0xf, true)); }
;     __device__ __forceinline__ void operator()(const f32x4 (&acc)[2][2][4][2], const Unit& u, int wr, int wc, int fr, int fq) const {
;     ...
;                         const float g = acc[ai][1][m][n][j];
;                         const float tp = l15 ? ((m > 0) ? acc[ai][1][m > 0 ? m - 1 : 0][n][j] : xp[n][j]) : g;
;                         const float tn = l0  ? ((m < 3) ? acc[ai][1][m < 3 ? m + 1 : 3][n][j] : xn[n][j]) : g;
;                         const float gp = ror1(tp), gn = ror15(tn);
;                         cv[4 * n + j] = fmaf(w0[n][j], gp, fmaf(w1[n][j], g, fmaf(w2[n][j], gn, bb[n][j])));
;                     }
;                 const int tr = ai * HALF + wr * 64 + m * 16 + fr;
;                 if (tr == 0 || tr == 255) { float* sb = SB + ((size_t)(u.pm * 2 + (tr ? 1 : 0)) * 3) * dff + ch0;
; #pragma unroll
;                     for (int n = 0; n < 2; ++n) { *(f32x4*)(sb + 4 * n) = (f32x4){cv[4 * n], cv[4 * n + 1], cv[4 * n + 2], cv[4 * n + 3]}; *(f32x4*)(sb + dff + 4 * n) = acc[ai][0][m][n]; *(f32x4*)(sb + 2 * dff + 4 * n) = acc[ai][1][m][n]; } }
;     ...
;                 for (int e = 0; e < 8; e += 2) { a[e] = go[e >> 1].x * acc[ai][0][m][e >> 2][e & 3]; a[e + 1] = go[e >> 1].y * acc[ai][0][m][(e + 1) >> 2][(e + 1) & 3]; }
;                 ow.x = cvt_pk_bf16(a[0], a[1]); ow.y = cvt_pk_bf16(a[2], a[3]); ow.z = cvt_pk_bf16(a[4], a[5]); ow.w = cvt_pk_bf16(a[6], a[7]);
;                 *(u32x4*)(ACT + (size_t)row * ldc + ch0) = ow;
	v_pk_fma_f32 v[174:175], v[150:151], v[174:175], s[10:11] op_sel_hi:[1,1,0]
	v_pk_fma_f32 v[160:161], v[154:155], v[160:161], s[10:11] op_sel_hi:[1,1,0]
	s_mov_b32 s10, 0x3e10c1ad
	v_mov_b32_dpp v117, v117 row_ror:1 row_mask:0xf bank_mask:0xf bound_ctrl:1
	v_pk_fma_f32 v[142:143], v[142:143], v[162:163], s[10:11] op_sel_hi:[1,1,0]
	v_pk_fma_f32 v[146:147], v[146:147], v[172:173], s[10:11] op_sel_hi:[1,1,0]
	v_pk_fma_f32 v[140:141], v[140:141], v[142:143], 0.5 op_sel_hi:[1,1,0]
	v_pk_fma_f32 v[150:151], v[150:151], v[174:175], s[10:11] op_sel_hi:[1,1,0]
	v_pk_mul_f32 v[136:137], v[136:137], v[140:141]
	v_pk_fma_f32 v[140:141], v[144:145], v[146:147], 0.5 op_sel_hi:[1,1,0]
	v_pk_fma_f32 v[154:155], v[154:155], v[160:161], s[10:11] op_sel_hi:[1,1,0]
	v_pk_mul_f32 v[138:139], v[138:139], v[140:141]
	v_pk_fma_f32 v[140:141], v[148:149], v[150:151], 0.5 op_sel_hi:[1,1,0]
	v_mul_f32_e32 v128, v128, v136
	v_pk_mul_f32 v[132:133], v[132:133], v[140:141]
	v_pk_fma_f32 v[140:141], v[152:153], v[154:155], 0.5 op_sel_hi:[1,1,0]
	v_mul_f32_e32 v129, v129, v137
	v_pk_mul_f32 v[134:135], v[134:135], v[140:141]
	v_mul_f32_e32 v132, v124, v132
	v_cvt_pk_bf16_f32 v124, v128, v129
	v_mad_i64_i32 v[128:129], s[10:11], v176, s3, v[158:159]
	v_mul_f32_e32 v130, v130, v138
	v_mul_f32_e32 v131, v131, v139
	v_mul_f32_e32 v133, v125, v133
	v_mul_f32_e32 v127, v127, v135
	v_cvt_pk_bf16_f32 v125, v130, v131
	v_lshl_add_u64 v[128:129], v[128:129], 0, v[156:157]
	v_mul_f32_e32 v134, v126, v134
	v_cvt_pk_bf16_f32 v126, v132, v133
	v_cvt_pk_bf16_f32 v127, v134, v127
	global_store_dwordx4 v[128:129], v[124:127], off nt
	v_cndmask_b32_e64 v118, v110, v118, s[40:41]
	v_cndmask_b32_e64 v119, v111, v119, s[40:41]
	v_cndmask_b32_e64 v124, v112, v168, s[38:39]
	v_cndmask_b32_e64 v125, v113, v169, s[38:39]
	v_mov_b32_dpp v118, v118 row_ror:1 row_mask:0xf bank_mask:0xf bound_ctrl:1
	v_mov_b32_dpp v124, v124 row_ror:15 row_mask:0xf bank_mask:0xf bound_ctrl:1
	v_mov_b32_dpp v125, v125 row_ror:15 row_mask:0xf bank_mask:0xf bound_ctrl:1
	v_pk_fma_f32 v[124:125], v[100:101], v[124:125], v[104:105]
	v_mov_b32_dpp v119, v119 row_ror:1 row_mask:0xf bank_mask:0xf bound_ctrl:1
	v_pk_fma_f32 v[124:125], v[96:97], v[112:113], v[124:125]
	s_movk_i32 s17, 0x2d00
	v_pk_fma_f32 v[120:121], v[92:93], v[120:121], v[124:125]
	v_cndmask_b32_e64 v124, v114, v170, s[38:39]
	v_cndmask_b32_e64 v125, v115, v171, s[38:39]
	s_nop 0
	v_mov_b32_dpp v124, v124 row_ror:15 row_mask:0xf bank_mask:0xf bound_ctrl:1
	v_mov_b32_dpp v125, v125 row_ror:15 row_mask:0xf bank_mask:0xf bound_ctrl:1
	v_pk_fma_f32 v[124:125], v[102:103], v[124:125], v[106:107]
	s_nop 0
	v_pk_fma_f32 v[124:125], v[98:99], v[114:115], v[124:125]
	s_nop 0
	v_pk_fma_f32 v[122:123], v[94:95], v[122:123], v[124:125]
	v_cndmask_b32_e64 v124, v108, v164, s[38:39]
	v_cndmask_b32_e64 v125, v109, v165, s[38:39]
	s_nop 0
	v_mov_b32_dpp v124, v124 row_ror:15 row_mask:0xf bank_mask:0xf bound_ctrl:1
	v_mov_b32_dpp v125, v125 row_ror:15 row_mask:0xf bank_mask:0xf bound_ctrl:1
	v_pk_fma_f32 v[124:125], v[84:85], v[124:125], v[88:89]
	s_nop 0
	v_pk_fma_f32 v[124:125], v[76:77], v[108:109], v[124:125]
	s_nop 0
	v_pk_fma_f32 v[116:117], v[72:73], v[116:117], v[124:125]
	v_cndmask_b32_e64 v124, v110, v166, s[38:39]
	v_cndmask_b32_e64 v125, v111, v167, s[38:39]
	s_nop 0
	v_mov_b32_dpp v124, v124 row_ror:15 row_mask:0xf bank_mask:0xf bound_ctrl:1
	v_mov_b32_dpp v125, v125 row_ror:15 row_mask:0xf bank_mask:0xf bound_ctrl:1
	v_pk_fma_f32 v[124:125], v[86:87], v[124:125], v[90:91]
	s_nop 0
	v_pk_fma_f32 v[124:125], v[78:79], v[110:111], v[124:125]
	s_nop 0
	v_pk_fma_f32 v[118:119], v[74:75], v[118:119], v[124:125]
	s_and_saveexec_b64 s[10:11], s[44:45]
	s_cbranch_execz .LBB0_1253
	s_or_b32 s15, s8, 1
	s_mul_hi_i32 s16, s15, 0x10800
	s_mul_i32 s15, s15, 0x10800
	s_add_u32 s20, s90, s15
	s_addc_u32 s21, s91, s16
	v_lshl_add_u64 v[124:125], v[190:191], 2, s[20:21]
	v_add_co_u32_e32 v126, vcc, 0x5000, v124
	global_store_dwordx4 v[124:125], v[120:123], off
	s_nop 0
	v_addc_co_u32_e32 v127, vcc, 0, v125, vcc
	v_add_co_u32_e32 v128, vcc, 0xb000, v124
	global_store_dwordx4 v[126:127], v[80:83], off offset:2048
	s_nop 0
	v_addc_co_u32_e32 v129, vcc, 0, v125, vcc
	global_store_dwordx4 v[128:129], v[112:115], off
	global_store_dwordx4 v[124:125], v[116:119], off offset:16
	global_store_dwordx4 v[126:127], v[68:71], off offset:2064
	global_store_dwordx4 v[128:129], v[108:111], off offset:16
; #define PG8_LAS __attribute__((address_space(3)))
; __device__ __forceinline__ unsigned cvt_pk_bf16(float lo, float hi) { unsigned r; asm volatile("v_cvt_pk_bf16_f32 %0, %1, %2" : "=v"(r) : "v"(lo), "v"(hi)); return r; }
;     __device__ __forceinline__ void operator()(const f32x4 (&acc)[2][2][4][2], const Unit& u, int wr, int wc, int fr, int fq) const {
;     ...
;             for (int n = 0; n < 2; ++n) { xp[n] = (f32x4){0.f, 0.f, 0.f, 0.f}; xn[n] = (f32x4){0.f, 0.f, 0.f, 0.f}; }
;             if (rp >= 0)  { const PG8_LAS float* s = XB + ((((rp >> 6) & 1) * 4 + wc) * 4 + (rp >> 7) * 2 + 1) * 32 + fq * 8; xp[0] = *(const PG8_LAS f32x4*)s; xp[1] = *(const PG8_LAS f32x4*)(s + 4); }
;             if (rn < 256) { const PG8_LAS float* s = XB + ((((rn >> 6) & 1) * 4 + wc) * 4 + (rn >> 7) * 2 + 0) * 32 + fq * 8; xn[0] = *(const PG8_LAS f32x4*)s; xn[1] = *(const PG8_LAS f32x4*)(s + 4); }
;     ...
;                 f32x2 gv[4], go[4]; float a[8];
; #pragma unroll
;                 for (int p = 0; p < 4; ++p) gv[p] = (f32x2){cv[2 * p], cv[2 * p + 1]};
;                 gelu4(gv, go);
; #pragma unroll
;                 for (int e = 0; e < 8; e += 2) { a[e] = go[e >> 1].x * acc[ai][0][m][e >> 2][e & 3]; a[e + 1] = go[e >> 1].y * acc[ai][0][m][(e + 1) >> 2][(e + 1) & 3]; }
;                 ow.x = cvt_pk_bf16(a[0], a[1]); ow.y = cvt_pk_bf16(a[2], a[3]); ow.z = cvt_pk_bf16(a[4], a[5]); ow.w = cvt_pk_bf16(a[6], a[7]);
;                 *(u32x4*)(ACT + (size_t)row * ldc + ch0) = ow;
.LBB0_1253:
	s_or_b64 exec, exec, s[10:11]
	s_nop 0
	v_med3_f32 v108, v120, s25, v248
	v_med3_f32 v109, v121, s25, v248
	v_pk_mul_f32 v[110:111], v[108:109], v[108:109]
	v_med3_f32 v112, v122, s25, v248
	v_med3_f32 v113, v123, s25, v248
	v_med3_f32 v124, v116, s25, v248
	v_med3_f32 v125, v117, s25, v248
	v_med3_f32 v128, v118, s25, v248
	v_med3_f32 v129, v119, s25, v248
	v_pk_fma_f32 v[110:111], v[110:111], s[14:15], -1.0 op_sel_hi:[1,0,0]
	v_pk_mul_f32 v[114:115], v[112:113], v[112:113]
	v_pk_mul_f32 v[126:127], v[124:125], v[124:125]
	v_pk_mul_f32 v[130:131], v[128:129], v[128:129]
	s_mov_b32 s10, 0x3a40c646
	s_mov_b32 s20, 0xffffffffbadbc5c1
	v_pk_fma_f32 v[114:115], v[114:115], s[14:15], -1.0 op_sel_hi:[1,0,0]
	v_mov_b64_e32 v[132:133], s[20:21]
	v_pk_fma_f32 v[126:127], v[126:127], s[14:15], -1.0 op_sel_hi:[1,0,0]
	v_pk_fma_f32 v[130:131], v[130:131], s[14:15], -1.0 op_sel_hi:[1,0,0]
	v_pk_fma_f32 v[134:135], v[110:111], s[10:11], v[132:133] op_sel_hi:[1,0,0]
	v_pk_fma_f32 v[136:137], v[114:115], s[10:11], v[132:133] op_sel_hi:[1,0,0]
	v_pk_fma_f32 v[138:139], v[126:127], s[10:11], v[132:133] op_sel_hi:[1,0,0]
	v_pk_fma_f32 v[132:133], v[130:131], s[10:11], v[132:133] op_sel_hi:[1,0,0]
	s_mov_b32 s10, 0x3ab42bcb
	v_or_b32_e32 v140, 48, v201
	v_pk_fma_f32 v[134:135], v[110:111], v[134:135], s[10:11] op_sel_hi:[1,1,0]
	v_pk_fma_f32 v[136:137], v[114:115], v[136:137], s[10:11] op_sel_hi:[1,1,0]
	v_pk_fma_f32 v[138:139], v[126:127], v[138:139], s[10:11] op_sel_hi:[1,1,0]
	v_pk_fma_f32 v[132:133], v[130:131], v[132:133], s[10:11] op_sel_hi:[1,1,0]
	s_mov_b32 s10, 0xffffffffbb259aa1
	s_andn2_b64 vcc, exec, s[62:63]
	v_pk_fma_f32 v[134:135], v[110:111], v[134:135], s[10:11] op_sel_hi:[1,1,0]
	v_pk_fma_f32 v[136:137], v[114:115], v[136:137], s[10:11] op_sel_hi:[1,1,0]
	v_pk_fma_f32 v[138:139], v[126:127], v[138:139], s[10:11] op_sel_hi:[1,1,0]
	v_pk_fma_f32 v[132:133], v[130:131], v[132:133], s[10:11] op_sel_hi:[1,1,0]
	s_mov_b32 s10, 0x3bddb9bf
	s_nop 0
	v_pk_fma_f32 v[134:135], v[110:111], v[134:135], s[10:11] op_sel_hi:[1,1,0]
	v_pk_fma_f32 v[136:137], v[114:115], v[136:137], s[10:11] op_sel_hi:[1,1,0]
	v_pk_fma_f32 v[138:139], v[126:127], v[138:139], s[10:11] op_sel_hi:[1,1,0]
	v_pk_fma_f32 v[132:133], v[130:131], v[132:133], s[10:11] op_sel_hi:[1,1,0]
	s_mov_b32 s10, 0xffffffffbc394185
	s_nop 0
	v_pk_fma_f32 v[134:135], v[110:111], v[134:135], s[10:11] op_sel_hi:[1,1,0]
	v_pk_fma_f32 v[136:137], v[114:115], v[136:137], s[10:11] op_sel_hi:[1,1,0]
	v_pk_fma_f32 v[138:139], v[126:127], v[138:139], s[10:11] op_sel_hi:[1,1,0]
	v_pk_fma_f32 v[132:133], v[130:131], v[132:133], s[10:11] op_sel_hi:[1,1,0]
	s_mov_b32 s10, 0x3c85018c
	s_nop 0
	v_pk_fma_f32 v[134:135], v[110:111], v[134:135], s[10:11] op_sel_hi:[1,1,0]
	v_pk_fma_f32 v[136:137], v[114:115], v[136:137], s[10:11] op_sel_hi:[1,1,0]
	v_pk_fma_f32 v[138:139], v[126:127], v[138:139], s[10:11] op_sel_hi:[1,1,0]
	v_pk_fma_f32 v[132:133], v[130:131], v[132:133], s[10:11] op_sel_hi:[1,1,0]
	s_mov_b32 s10, 0xffffffffbcbe2975
	s_nop 0
	v_pk_fma_f32 v[134:135], v[110:111], v[134:135], s[10:11] op_sel_hi:[1,1,0]
	v_pk_fma_f32 v[136:137], v[114:115], v[136:137], s[10:11] op_sel_hi:[1,1,0]
	v_pk_fma_f32 v[138:139], v[126:127], v[138:139], s[10:11] op_sel_hi:[1,1,0]
	v_pk_fma_f32 v[132:133], v[130:131], v[132:133], s[10:11] op_sel_hi:[1,1,0]
	s_mov_b32 s10, 0x3d00edc6
	s_nop 0
	v_pk_fma_f32 v[134:135], v[110:111], v[134:135], s[10:11] op_sel_hi:[1,1,0]
	v_pk_fma_f32 v[136:137], v[114:115], v[136:137], s[10:11] op_sel_hi:[1,1,0]
	v_pk_fma_f32 v[138:139], v[126:127], v[138:139], s[10:11] op_sel_hi:[1,1,0]
	v_pk_fma_f32 v[132:133], v[130:131], v[132:133], s[10:11] op_sel_hi:[1,1,0]
	s_mov_b32 s10, 0xffffffffbd25b03e
	s_nop 0
	v_pk_fma_f32 v[134:135], v[110:111], v[134:135], s[10:11] op_sel_hi:[1,1,0]
	v_pk_fma_f32 v[136:137], v[114:115], v[136:137], s[10:11] op_sel_hi:[1,1,0]
	v_pk_fma_f32 v[138:139], v[126:127], v[138:139], s[10:11] op_sel_hi:[1,1,0]
	v_pk_fma_f32 v[132:133], v[130:131], v[132:133], s[10:11] op_sel_hi:[1,1,0]
	s_mov_b32 s10, 0x3d530477
	s_nop 0
	v_pk_fma_f32 v[134:135], v[110:111], v[134:135], s[10:11] op_sel_hi:[1,1,0]
	v_pk_fma_f32 v[136:137], v[114:115], v[136:137], s[10:11] op_sel_hi:[1,1,0]
	v_pk_fma_f32 v[138:139], v[126:127], v[138:139], s[10:11] op_sel_hi:[1,1,0]
	v_pk_fma_f32 v[132:133], v[130:131], v[132:133], s[10:11] op_sel_hi:[1,1,0]
	s_mov_b32 s10, 0xffffffffbd8ff74d
	s_nop 0
	v_pk_fma_f32 v[134:135], v[110:111], v[134:135], s[10:11] op_sel_hi:[1,1,0]
	v_pk_fma_f32 v[136:137], v[114:115], v[136:137], s[10:11] op_sel_hi:[1,1,0]
	v_pk_fma_f32 v[138:139], v[126:127], v[138:139], s[10:11] op_sel_hi:[1,1,0]
	v_pk_fma_f32 v[132:133], v[130:131], v[132:133], s[10:11] op_sel_hi:[1,1,0]
	s_mov_b32 s10, 0x3e10c1ad
	s_nop 0
	v_pk_fma_f32 v[110:111], v[110:111], v[134:135], s[10:11] op_sel_hi:[1,1,0]
	v_pk_fma_f32 v[114:115], v[114:115], v[136:137], s[10:11] op_sel_hi:[1,1,0]
	v_pk_fma_f32 v[126:127], v[126:127], v[138:139], s[10:11] op_sel_hi:[1,1,0]
	v_pk_fma_f32 v[108:109], v[108:109], v[110:111], 0.5 op_sel_hi:[1,1,0]
	v_pk_fma_f32 v[110:111], v[112:113], v[114:115], 0.5 op_sel_hi:[1,1,0]
	v_pk_mul_f32 v[108:109], v[120:121], v[108:109]
	v_pk_fma_f32 v[112:113], v[124:125], v[126:127], 0.5 op_sel_hi:[1,1,0]
	v_pk_fma_f32 v[130:131], v[130:131], v[132:133], s[10:11] op_sel_hi:[1,1,0]
	v_pk_mul_f32 v[112:113], v[116:117], v[112:113]
	v_mul_f32_e32 v80, v80, v108
	v_mul_f32_e32 v81, v81, v109
	v_pk_fma_f32 v[114:115], v[128:129], v[130:131], 0.5 op_sel_hi:[1,1,0]
	v_mul_f32_e32 v108, v68, v112
	v_cvt_pk_bf16_f32 v68, v80, v81
	v_mov_b64_e32 v[80:81], s[54:55]
	v_pk_mul_f32 v[110:111], v[122:123], v[110:111]
	v_pk_mul_f32 v[114:115], v[118:119], v[114:115]
	v_mad_i64_i32 v[80:81], s[10:11], v140, s17, v[80:81]
	v_mul_f32_e32 v82, v82, v110
	v_mul_f32_e32 v109, v69, v113
	v_mul_f32_e32 v110, v70, v114
	v_mul_f32_e32 v71, v71, v115
	v_lshl_add_u64 v[80:81], v[190:191], 1, v[80:81]
	v_mul_f32_e32 v83, v83, v111
	v_cvt_pk_bf16_f32 v69, v82, v83
	v_cvt_pk_bf16_f32 v70, v108, v109
	v_cvt_pk_bf16_f32 v71, v110, v71
	global_store_dwordx4 v[80:81], v[68:71], off nt
	v_mov_b32_e32 v112, 0
	v_mov_b32_e32 v113, 0
	v_mov_b32_e32 v68, 0
	v_mov_b32_e32 v114, 0
	v_mov_b32_e32 v115, 0
	v_mov_b32_e32 v108, 0
	v_mov_b32_e32 v109, 0
	v_mov_b32_e32 v110, 0
	v_mov_b32_e32 v111, 0
	s_cbranch_vccnz .LBB0_1255
	ds_read_b128 v[108:111], v197 offset:128
	ds_read_b128 v[112:115], v197 offset:144

; __device__ __forceinline__ void gelu4(const f32x2 (&v)[4], f32x2 (&o)[4]) {
;     ...
;     for (int p = 0; p < 4; ++p) { c[p].x = __builtin_amdgcn_fmed3f(v[p].x, -5.0f, 5.0f); c[p].y = __builtin_amdgcn_fmed3f(v[p].y, -5.0f, 5.0f); w[p] = (c[p] * c[p]) * 0.08f + (-1.0f); }
;     { const float ka = kc<0x3a40c646u>(), kb = kc<0xbadbc5c1u>();
; #pragma unroll
;       for (int p = 0; p < 4; ++p) q[p] = w[p] * ka + kb; }
;     { const float kk = kc<0x3ab42bcbu>();
; #pragma unroll
;       for (int p = 0; p < 4; ++p) q[p] = q[p] * w[p] + kk; }
;     { const float kk = kc<0xbb259aa1u>();
; #pragma unroll
;       for (int p = 0; p < 4; ++p) q[p] = q[p] * w[p] + kk; }
;     { const float kk = kc<0x3bddb9bfu>();
; #pragma unroll
;       for (int p = 0; p < 4; ++p) q[p] = q[p] * w[p] + kk; }
;     { const float kk = kc<0xbc394185u>();
; #pragma unroll
;       for (int p = 0; p < 4; ++p) q[p] = q[p] * w[p] + kk; }
;     { const float kk = kc<0x3c85018cu>();
; #pragma unroll
;       for (int p = 0; p < 4; ++p) q[p] = q[p] * w[p] + kk; }
;     { const float kk = kc<0xbcbe2975u>();
; #pragma unroll
;       for (int p = 0; p < 4; ++p) q[p] = q[p] * w[p] + kk; }
;     { const float kk = kc<0x3d00edc6u>();
; #pragma unroll
;       for (int p = 0; p < 4; ++p) q[p] = q[p] * w[p] + kk; }
;     { const float kk = kc<0xbd25b03eu>();
; #pragma unroll
;       for (int p = 0; p < 4; ++p) q[p] = q[p] * w[p] + kk; }
;     { const float kk = kc<0x3d530477u>();
; #pragma unroll
;       for (int p = 0; p < 4; ++p) q[p] = q[p] * w[p] + kk; }
;     { const float kk = kc<0xbd8ff74du>();
; #pragma unroll
;       for (int p = 0; p < 4; ++p) q[p] = q[p] * w[p] + kk; }
;     { const float kk = kc<0x3e10c1adu>();
; #pragma unroll
;       for (int p = 0; p < 4; ++p) q[p] = q[p] * w[p] + kk; }
; #pragma unroll
;     for (int p = 0; p < 4; ++p) o[p] = v[p] * (q[p] * c[p] + 0.5f);
;     __device__ __forceinline__ void operator()(const f32x4 (&acc)[2][2][4][2], const Unit& u, int wr, int wc, int fr, int fq) const {
;     ...
;                         const float g = acc[ai][1][m][n][j];
;                         const float tp = l15 ? ((m > 0) ? acc[ai][1][m > 0 ? m - 1 : 0][n][j] : xp[n][j]) : g;
;                         const float tn = l0  ? ((m < 3) ? acc[ai][1][m < 3 ? m + 1 : 3][n][j] : xn[n][j]) : g;
;                         const float gp = ror1(tp), gn = ror15(tn);
.LBB0_1259:
	s_or_b64 exec, exec, s[10:11]
	v_med3_f32 v116, v108, s25, v248
	v_med3_f32 v117, v109, s25, v248
	v_pk_mul_f32 v[118:119], v[116:117], v[116:117]
	v_med3_f32 v120, v110, s25, v248
	v_med3_f32 v121, v111, s25, v248
	v_med3_f32 v124, v112, s25, v248
	v_med3_f32 v125, v113, s25, v248
	v_med3_f32 v128, v114, s25, v248
	v_med3_f32 v129, v115, s25, v248
	v_pk_fma_f32 v[118:119], v[118:119], s[14:15], -1.0 op_sel_hi:[1,0,0]
	v_pk_mul_f32 v[122:123], v[120:121], v[120:121]
	v_pk_mul_f32 v[126:127], v[124:125], v[124:125]
	v_pk_mul_f32 v[130:131], v[128:129], v[128:129]
	s_mov_b32 s10, 0x3a40c646
	s_mov_b32 s18, 0xffffffffbadbc5c1
	v_pk_fma_f32 v[122:123], v[122:123], s[14:15], -1.0 op_sel_hi:[1,0,0]
	v_mov_b64_e32 v[132:133], s[18:19]
	v_pk_fma_f32 v[126:127], v[126:127], s[14:15], -1.0 op_sel_hi:[1,0,0]
	v_pk_fma_f32 v[130:131], v[130:131], s[14:15], -1.0 op_sel_hi:[1,0,0]
	v_pk_fma_f32 v[134:135], v[118:119], s[10:11], v[132:133] op_sel_hi:[1,0,0]
	v_pk_fma_f32 v[136:137], v[122:123], s[10:11], v[132:133] op_sel_hi:[1,0,0]
	v_pk_fma_f32 v[138:139], v[126:127], s[10:11], v[132:133] op_sel_hi:[1,0,0]
	v_pk_fma_f32 v[132:133], v[130:131], s[10:11], v[132:133] op_sel_hi:[1,0,0]
	s_mov_b32 s10, 0x3ab42bcb
	v_add_u32_e32 v140, 0x80, v201
	v_pk_fma_f32 v[134:135], v[118:119], v[134:135], s[10:11] op_sel_hi:[1,1,0]
	v_pk_fma_f32 v[136:137], v[122:123], v[136:137], s[10:11] op_sel_hi:[1,1,0]
	v_pk_fma_f32 v[138:139], v[126:127], v[138:139], s[10:11] op_sel_hi:[1,1,0]
	v_pk_fma_f32 v[132:133], v[130:131], v[132:133], s[10:11] op_sel_hi:[1,1,0]
	s_mov_b32 s10, 0xffffffffbb259aa1
	v_cndmask_b32_e64 v56, v40, v56, s[40:41]
	v_pk_fma_f32 v[134:135], v[118:119], v[134:135], s[10:11] op_sel_hi:[1,1,0]
	v_pk_fma_f32 v[136:137], v[122:123], v[136:137], s[10:11] op_sel_hi:[1,1,0]
	v_pk_fma_f32 v[138:139], v[126:127], v[138:139], s[10:11] op_sel_hi:[1,1,0]
	v_pk_fma_f32 v[132:133], v[130:131], v[132:133], s[10:11] op_sel_hi:[1,1,0]
	s_mov_b32 s10, 0x3bddb9bf
	v_cndmask_b32_e64 v57, v41, v57, s[40:41]
	v_pk_fma_f32 v[134:135], v[118:119], v[134:135], s[10:11] op_sel_hi:[1,1,0]
	v_pk_fma_f32 v[136:137], v[122:123], v[136:137], s[10:11] op_sel_hi:[1,1,0]
	v_pk_fma_f32 v[138:139], v[126:127], v[138:139], s[10:11] op_sel_hi:[1,1,0]
	v_pk_fma_f32 v[132:133], v[130:131], v[132:133], s[10:11] op_sel_hi:[1,1,0]
	s_mov_b32 s10, 0xffffffffbc394185
	v_mov_b32_dpp v56, v56 row_ror:1 row_mask:0xf bank_mask:0xf bound_ctrl:1
	v_pk_fma_f32 v[134:135], v[118:119], v[134:135], s[10:11] op_sel_hi:[1,1,0]
	v_pk_fma_f32 v[136:137], v[122:123], v[136:137], s[10:11] op_sel_hi:[1,1,0]
	v_pk_fma_f32 v[138:139], v[126:127], v[138:139], s[10:11] op_sel_hi:[1,1,0]
	v_pk_fma_f32 v[132:133], v[130:131], v[132:133], s[10:11] op_sel_hi:[1,1,0]
	s_mov_b32 s10, 0x3c85018c
	v_mov_b32_dpp v57, v57 row_ror:1 row_mask:0xf bank_mask:0xf bound_ctrl:1
	v_pk_fma_f32 v[134:135], v[118:119], v[134:135], s[10:11] op_sel_hi:[1,1,0]
	v_pk_fma_f32 v[136:137], v[122:123], v[136:137], s[10:11] op_sel_hi:[1,1,0]
	v_pk_fma_f32 v[138:139], v[126:127], v[138:139], s[10:11] op_sel_hi:[1,1,0]
	v_pk_fma_f32 v[132:133], v[130:131], v[132:133], s[10:11] op_sel_hi:[1,1,0]
	s_mov_b32 s10, 0xffffffffbcbe2975
	v_cndmask_b32_e64 v58, v42, v58, s[40:41]
	v_pk_fma_f32 v[134:135], v[118:119], v[134:135], s[10:11] op_sel_hi:[1,1,0]
	v_pk_fma_f32 v[136:137], v[122:123], v[136:137], s[10:11] op_sel_hi:[1,1,0]
	v_pk_fma_f32 v[138:139], v[126:127], v[138:139], s[10:11] op_sel_hi:[1,1,0]
	v_pk_fma_f32 v[132:133], v[130:131], v[132:133], s[10:11] op_sel_hi:[1,1,0]
	s_mov_b32 s10, 0x3d00edc6
	v_cndmask_b32_e64 v59, v43, v59, s[40:41]
	v_pk_fma_f32 v[134:135], v[118:119], v[134:135], s[10:11] op_sel_hi:[1,1,0]
	v_pk_fma_f32 v[136:137], v[122:123], v[136:137], s[10:11] op_sel_hi:[1,1,0]
	v_pk_fma_f32 v[138:139], v[126:127], v[138:139], s[10:11] op_sel_hi:[1,1,0]
	v_pk_fma_f32 v[132:133], v[130:131], v[132:133], s[10:11] op_sel_hi:[1,1,0]
	s_mov_b32 s10, 0xffffffffbd25b03e
	v_mov_b32_dpp v58, v58 row_ror:1 row_mask:0xf bank_mask:0xf bound_ctrl:1
	v_pk_fma_f32 v[134:135], v[118:119], v[134:135], s[10:11] op_sel_hi:[1,1,0]
	v_pk_fma_f32 v[136:137], v[122:123], v[136:137], s[10:11] op_sel_hi:[1,1,0]
	v_pk_fma_f32 v[138:139], v[126:127], v[138:139], s[10:11] op_sel_hi:[1,1,0]
	v_pk_fma_f32 v[132:133], v[130:131], v[132:133], s[10:11] op_sel_hi:[1,1,0]
	s_mov_b32 s10, 0x3d530477
	v_mov_b32_dpp v59, v59 row_ror:1 row_mask:0xf bank_mask:0xf bound_ctrl:1
	v_pk_fma_f32 v[134:135], v[118:119], v[134:135], s[10:11] op_sel_hi:[1,1,0]
	v_pk_fma_f32 v[136:137], v[122:123], v[136:137], s[10:11] op_sel_hi:[1,1,0]
	v_pk_fma_f32 v[138:139], v[126:127], v[138:139], s[10:11] op_sel_hi:[1,1,0]
	v_pk_fma_f32 v[132:133], v[130:131], v[132:133], s[10:11] op_sel_hi:[1,1,0]
	s_mov_b32 s10, 0xffffffffbd8ff74d
	v_cndmask_b32_e64 v52, v36, v52, s[40:41]
	v_pk_fma_f32 v[134:135], v[118:119], v[134:135], s[10:11] op_sel_hi:[1,1,0]
	v_pk_fma_f32 v[136:137], v[122:123], v[136:137], s[10:11] op_sel_hi:[1,1,0]
	v_pk_fma_f32 v[138:139], v[126:127], v[138:139], s[10:11] op_sel_hi:[1,1,0]
	v_pk_fma_f32 v[132:133], v[130:131], v[132:133], s[10:11] op_sel_hi:[1,1,0]
	s_mov_b32 s10, 0x3e10c1ad
	v_cndmask_b32_e64 v53, v37, v53, s[40:41]
	v_pk_fma_f32 v[118:119], v[118:119], v[134:135], s[10:11] op_sel_hi:[1,1,0]
	v_pk_fma_f32 v[122:123], v[122:123], v[136:137], s[10:11] op_sel_hi:[1,1,0]
	v_pk_fma_f32 v[116:117], v[116:117], v[118:119], 0.5 op_sel_hi:[1,1,0]
	v_pk_fma_f32 v[126:127], v[126:127], v[138:139], s[10:11] op_sel_hi:[1,1,0]
	v_pk_mul_f32 v[108:109], v[108:109], v[116:117]
	v_pk_fma_f32 v[116:117], v[120:121], v[122:123], 0.5 op_sel_hi:[1,1,0]
; __device__ __forceinline__ unsigned cvt_pk_bf16(float lo, float hi) { unsigned r; asm volatile("v_cvt_pk_bf16_f32 %0, %1, %2" : "=v"(r) : "v"(lo), "v"(hi)); return r; }
;     static __device__ __forceinline__ float ror1(float v)  { return __builtin_bit_cast(float, __builtin_amdgcn_update_dpp(0, __builtin_bit_cast(int, v), 0x121, 0xf, 0xf, true)); }
;     static __device__ __forceinline__ float ror15(float v) { return __builtin_bit_cast(float, __builtin_amdgcn_update_dpp(0, __builtin_bit_cast(int, v), 0x12f, 0xf, 0xf, true)); }
;     __device__ __forceinline__ void operator()(const f32x4 (&acc)[2][2][4][2], const Unit& u, int wr, int wc, int fr, int fq) const {
;     ...
;                         const float g = acc[ai][1][m][n][j];
;                         const float tp = l15 ? ((m > 0) ? acc[ai][1][m > 0 ? m - 1 : 0][n][j] : xp[n][j]) : g;
;                         const float tn = l0  ? ((m < 3) ? acc[ai][1][m < 3 ? m + 1 : 3][n][j] : xn[n][j]) : g;
;                         const float gp = ror1(tp), gn = ror15(tn);
;                         cv[4 * n + j] = fmaf(w0[n][j], gp, fmaf(w1[n][j], g, fmaf(w2[n][j], gn, bb[n][j])));
;     ...
;                 f32x2 gv[4], go[4]; float a[8];
; #pragma unroll
;                 for (int p = 0; p < 4; ++p) gv[p] = (f32x2){cv[2 * p], cv[2 * p + 1]};
;                 gelu4(gv, go);
; #pragma unroll
;                 for (int e = 0; e < 8; e += 2) { a[e] = go[e >> 1].x * acc[ai][0][m][e >> 2][e & 3]; a[e + 1] = go[e >> 1].y * acc[ai][0][m][(e + 1) >> 2][(e + 1) & 3]; }
;                 ow.x = cvt_pk_bf16(a[0], a[1]); ow.y = cvt_pk_bf16(a[2], a[3]); ow.z = cvt_pk_bf16(a[4], a[5]); ow.w = cvt_pk_bf16(a[6], a[7]);
;                 *(u32x4*)(ACT + (size_t)row * ldc + ch0) = ow;
	v_pk_fma_f32 v[130:131], v[130:131], v[132:133], s[10:11] op_sel_hi:[1,1,0]
	v_pk_mul_f32 v[110:111], v[110:111], v[116:117]
	v_pk_fma_f32 v[116:117], v[124:125], v[126:127], 0.5 op_sel_hi:[1,1,0]
	v_mul_f32_e32 v64, v64, v108
	v_pk_mul_f32 v[112:113], v[112:113], v[116:117]
	v_pk_fma_f32 v[116:117], v[128:129], v[130:131], 0.5 op_sel_hi:[1,1,0]
	v_mul_f32_e32 v60, v60, v112
	v_pk_mul_f32 v[114:115], v[114:115], v[116:117]
	v_mul_f32_e32 v61, v61, v113
	v_mul_f32_e32 v65, v65, v109
	v_mul_f32_e32 v66, v66, v110
	v_mul_f32_e32 v67, v67, v111
	v_mul_f32_e32 v108, v62, v114
	v_mul_f32_e32 v109, v63, v115
	v_cvt_pk_bf16_f32 v62, v64, v65
	v_cvt_pk_bf16_f32 v63, v66, v67
	v_cvt_pk_bf16_f32 v64, v60, v61
	v_mov_b64_e32 v[60:61], s[54:55]
	v_mad_i64_i32 v[66:67], s[10:11], v140, s3, v[60:61]
	v_lshl_add_u64 v[66:67], v[66:67], 0, v[156:157]
	v_cvt_pk_bf16_f32 v65, v108, v109
	global_store_dwordx4 v[66:67], v[62:65], off nt
	v_mov_b32_dpp v52, v52 row_ror:1 row_mask:0xf bank_mask:0xf bound_ctrl:1
	v_mov_b32_dpp v53, v53 row_ror:1 row_mask:0xf bank_mask:0xf bound_ctrl:1
	v_cndmask_b32_e64 v62, v40, v24, s[38:39]
	v_cndmask_b32_e64 v63, v41, v25, s[38:39]
	v_cndmask_b32_e64 v54, v38, v54, s[40:41]
	v_mov_b32_dpp v62, v62 row_ror:15 row_mask:0xf bank_mask:0xf bound_ctrl:1
	v_mov_b32_dpp v63, v63 row_ror:15 row_mask:0xf bank_mask:0xf bound_ctrl:1
	v_pk_fma_f32 v[62:63], v[100:101], v[62:63], v[104:105]
	v_cndmask_b32_e64 v55, v39, v55, s[40:41]
	v_pk_fma_f32 v[62:63], v[96:97], v[40:41], v[62:63]
	v_mov_b32_dpp v54, v54 row_ror:1 row_mask:0xf bank_mask:0xf bound_ctrl:1
	v_pk_fma_f32 v[56:57], v[92:93], v[56:57], v[62:63]
	v_cndmask_b32_e64 v62, v42, v26, s[38:39]
	v_cndmask_b32_e64 v63, v43, v27, s[38:39]
	v_mov_b32_dpp v55, v55 row_ror:1 row_mask:0xf bank_mask:0xf bound_ctrl:1
	v_mov_b32_dpp v62, v62 row_ror:15 row_mask:0xf bank_mask:0xf bound_ctrl:1
	v_mov_b32_dpp v63, v63 row_ror:15 row_mask:0xf bank_mask:0xf bound_ctrl:1
	v_pk_fma_f32 v[62:63], v[102:103], v[62:63], v[106:107]
	s_mov_b32 s10, 0x3a40c646
	s_mov_b32 s18, 0xffffffffbadbc5c1
	v_add_u32_e32 v126, 0x90, v201
	v_pk_fma_f32 v[62:63], v[98:99], v[42:43], v[62:63]
	v_mov_b64_e32 v[118:119], s[18:19]
	v_pk_fma_f32 v[58:59], v[94:95], v[58:59], v[62:63]
	v_cndmask_b32_e64 v62, v36, v20, s[38:39]
	v_cndmask_b32_e64 v63, v37, v21, s[38:39]
	v_med3_f32 v66, v58, s25, v248
	v_mov_b32_dpp v62, v62 row_ror:15 row_mask:0xf bank_mask:0xf bound_ctrl:1
	v_mov_b32_dpp v63, v63 row_ror:15 row_mask:0xf bank_mask:0xf bound_ctrl:1
	v_pk_fma_f32 v[62:63], v[84:85], v[62:63], v[88:89]
	v_med3_f32 v67, v59, s25, v248
	v_pk_fma_f32 v[62:63], v[76:77], v[36:37], v[62:63]
	v_pk_mul_f32 v[108:109], v[66:67], v[66:67]
	v_pk_fma_f32 v[52:53], v[72:73], v[52:53], v[62:63]
	v_cndmask_b32_e64 v62, v38, v22, s[38:39]
	v_cndmask_b32_e64 v63, v39, v23, s[38:39]
	v_med3_f32 v110, v52, s25, v248
	v_mov_b32_dpp v62, v62 row_ror:15 row_mask:0xf bank_mask:0xf bound_ctrl:1
	v_mov_b32_dpp v63, v63 row_ror:15 row_mask:0xf bank_mask:0xf bound_ctrl:1
	v_pk_fma_f32 v[62:63], v[86:87], v[62:63], v[90:91]
	v_med3_f32 v111, v53, s25, v248
	v_pk_fma_f32 v[62:63], v[78:79], v[38:39], v[62:63]
	v_pk_mul_f32 v[112:113], v[110:111], v[110:111]
	v_pk_fma_f32 v[54:55], v[74:75], v[54:55], v[62:63]
	v_med3_f32 v62, v56, s25, v248
	v_med3_f32 v63, v57, s25, v248
	v_pk_mul_f32 v[64:65], v[62:63], v[62:63]
	v_med3_f32 v114, v54, s25, v248
	v_med3_f32 v115, v55, s25, v248
	v_pk_fma_f32 v[64:65], v[64:65], s[14:15], -1.0 op_sel_hi:[1,0,0]
	v_pk_mul_f32 v[116:117], v[114:115], v[114:115]
	v_pk_fma_f32 v[108:109], v[108:109], s[14:15], -1.0 op_sel_hi:[1,0,0]
	v_pk_fma_f32 v[112:113], v[112:113], s[14:15], -1.0 op_sel_hi:[1,0,0]
	v_pk_fma_f32 v[116:117], v[116:117], s[14:15], -1.0 op_sel_hi:[1,0,0]
	v_pk_fma_f32 v[120:121], v[64:65], s[10:11], v[118:119] op_sel_hi:[1,0,0]
	v_pk_fma_f32 v[122:123], v[108:109], s[10:11], v[118:119] op_sel_hi:[1,0,0]
	v_pk_fma_f32 v[124:125], s[10:11], v[112:113], v[118:119] op_sel_hi:[0,1,0]
	v_pk_fma_f32 v[118:119], s[10:11], v[116:117], v[118:119] op_sel_hi:[0,1,0]
	s_mov_b32 s10, 0x3ab42bcb
	v_cndmask_b32_e64 v40, v24, v40, s[40:41]
	v_pk_fma_f32 v[120:121], v[64:65], v[120:121], s[10:11] op_sel_hi:[1,1,0]
	v_pk_fma_f32 v[122:123], v[108:109], v[122:123], s[10:11] op_sel_hi:[1,1,0]
	v_pk_fma_f32 v[124:125], v[112:113], v[124:125], s[10:11] op_sel_hi:[1,1,0]
	v_pk_fma_f32 v[118:119], v[116:117], v[118:119], s[10:11] op_sel_hi:[1,1,0]
	s_mov_b32 s10, 0xffffffffbb259aa1
	v_cndmask_b32_e64 v41, v25, v41, s[40:41]
	v_pk_fma_f32 v[120:121], v[64:65], v[120:121], s[10:11] op_sel_hi:[1,1,0]
	v_pk_fma_f32 v[122:123], v[108:109], v[122:123], s[10:11] op_sel_hi:[1,1,0]
	v_pk_fma_f32 v[124:125], v[112:113], v[124:125], s[10:11] op_sel_hi:[1,1,0]
	v_pk_fma_f32 v[118:119], v[116:117], v[118:119], s[10:11] op_sel_hi:[1,1,0]
	s_mov_b32 s10, 0x3bddb9bf
	v_mov_b32_dpp v40, v40 row_ror:1 row_mask:0xf bank_mask:0xf bound_ctrl:1
	v_pk_fma_f32 v[120:121], v[64:65], v[120:121], s[10:11] op_sel_hi:[1,1,0]
	v_pk_fma_f32 v[122:123], v[108:109], v[122:123], s[10:11] op_sel_hi:[1,1,0]
	v_pk_fma_f32 v[124:125], v[112:113], v[124:125], s[10:11] op_sel_hi:[1,1,0]
	v_pk_fma_f32 v[118:119], v[116:117], v[118:119], s[10:11] op_sel_hi:[1,1,0]
	s_mov_b32 s10, 0xffffffffbc394185
	v_mov_b32_dpp v41, v41 row_ror:1 row_mask:0xf bank_mask:0xf bound_ctrl:1
	v_pk_fma_f32 v[120:121], v[64:65], v[120:121], s[10:11] op_sel_hi:[1,1,0]
	v_pk_fma_f32 v[122:123], v[108:109], v[122:123], s[10:11] op_sel_hi:[1,1,0]
	v_pk_fma_f32 v[124:125], v[112:113], v[124:125], s[10:11] op_sel_hi:[1,1,0]
	v_pk_fma_f32 v[118:119], v[116:117], v[118:119], s[10:11] op_sel_hi:[1,1,0]
; __device__ __forceinline__ void gelu4(const f32x2 (&v)[4], f32x2 (&o)[4]) {
;     ...
;     for (int p = 0; p < 4; ++p) { c[p].x = __builtin_amdgcn_fmed3f(v[p].x, -5.0f, 5.0f); c[p].y = __builtin_amdgcn_fmed3f(v[p].y, -5.0f, 5.0f); w[p] = (c[p] * c[p]) * 0.08f + (-1.0f); }
;     { const float ka = kc<0x3a40c646u>(), kb = kc<0xbadbc5c1u>();
; #pragma unroll
;       for (int p = 0; p < 4; ++p) q[p] = w[p] * ka + kb; }
;     { const float kk = kc<0x3ab42bcbu>();
; #pragma unroll
;       for (int p = 0; p < 4; ++p) q[p] = q[p] * w[p] + kk; }
;     { const float kk = kc<0xbb259aa1u>();
; #pragma unroll
;       for (int p = 0; p < 4; ++p) q[p] = q[p] * w[p] + kk; }
;     { const float kk = kc<0x3bddb9bfu>();
; #pragma unroll
;       for (int p = 0; p < 4; ++p) q[p] = q[p] * w[p] + kk; }
;     { const float kk = kc<0xbc394185u>();
; #pragma unroll
;       for (int p = 0; p < 4; ++p) q[p] = q[p] * w[p] + kk; }
;     { const float kk = kc<0x3c85018cu>();
; #pragma unroll
;       for (int p = 0; p < 4; ++p) q[p] = q[p] * w[p] + kk; }
;     { const float kk = kc<0xbcbe2975u>();
; #pragma unroll
;       for (int p = 0; p < 4; ++p) q[p] = q[p] * w[p] + kk; }
;     { const float kk = kc<0x3d00edc6u>();
; #pragma unroll
;       for (int p = 0; p < 4; ++p) q[p] = q[p] * w[p] + kk; }
;     { const float kk = kc<0xbd25b03eu>();
; #pragma unroll
;       for (int p = 0; p < 4; ++p) q[p] = q[p] * w[p] + kk; }
;     { const float kk = kc<0x3d530477u>();
; #pragma unroll
;       for (int p = 0; p < 4; ++p) q[p] = q[p] * w[p] + kk; }
;     { const float kk = kc<0xbd8ff74du>();
; #pragma unroll
;       for (int p = 0; p < 4; ++p) q[p] = q[p] * w[p] + kk; }
;     { const float kk = kc<0x3e10c1adu>();
; #pragma unroll
;       for (int p = 0; p < 4; ++p) q[p] = q[p] * w[p] + kk; }
; #pragma unroll
;     for (int p = 0; p < 4; ++p) o[p] = v[p] * (q[p] * c[p] + 0.5f);
;     __device__ __forceinline__ void operator()(const f32x4 (&acc)[2][2][4][2], const Unit& u, int wr, int wc, int fr, int fq) const {
;     ...
;                         const float g = acc[ai][1][m][n][j];
;                         const float tp = l15 ? ((m > 0) ? acc[ai][1][m > 0 ? m - 1 : 0][n][j] : xp[n][j]) : g;
;                         const float tn = l0  ? ((m < 3) ? acc[ai][1][m < 3 ? m + 1 : 3][n][j] : xn[n][j]) : g;
;                         const float gp = ror1(tp), gn = ror15(tn);
	s_mov_b32 s10, 0x3c85018c
	v_cndmask_b32_e64 v42, v26, v42, s[40:41]
	v_pk_fma_f32 v[120:121], v[64:65], v[120:121], s[10:11] op_sel_hi:[1,1,0]
	v_pk_fma_f32 v[122:123], v[108:109], v[122:123], s[10:11] op_sel_hi:[1,1,0]
	v_pk_fma_f32 v[124:125], v[112:113], v[124:125], s[10:11] op_sel_hi:[1,1,0]
	v_pk_fma_f32 v[118:119], v[116:117], v[118:119], s[10:11] op_sel_hi:[1,1,0]
	s_mov_b32 s10, 0xffffffffbcbe2975
	v_cndmask_b32_e64 v43, v27, v43, s[40:41]
	v_pk_fma_f32 v[120:121], v[64:65], v[120:121], s[10:11] op_sel_hi:[1,1,0]
	v_pk_fma_f32 v[122:123], v[108:109], v[122:123], s[10:11] op_sel_hi:[1,1,0]
	v_pk_fma_f32 v[124:125], v[112:113], v[124:125], s[10:11] op_sel_hi:[1,1,0]
	v_pk_fma_f32 v[118:119], v[116:117], v[118:119], s[10:11] op_sel_hi:[1,1,0]
	s_mov_b32 s10, 0x3d00edc6
	v_mov_b32_dpp v42, v42 row_ror:1 row_mask:0xf bank_mask:0xf bound_ctrl:1
	v_pk_fma_f32 v[120:121], v[64:65], v[120:121], s[10:11] op_sel_hi:[1,1,0]
	v_pk_fma_f32 v[122:123], v[108:109], v[122:123], s[10:11] op_sel_hi:[1,1,0]
	v_pk_fma_f32 v[124:125], v[112:113], v[124:125], s[10:11] op_sel_hi:[1,1,0]
	v_pk_fma_f32 v[118:119], v[116:117], v[118:119], s[10:11] op_sel_hi:[1,1,0]
	s_mov_b32 s10, 0xffffffffbd25b03e
	v_mov_b32_dpp v43, v43 row_ror:1 row_mask:0xf bank_mask:0xf bound_ctrl:1
	v_pk_fma_f32 v[120:121], v[64:65], v[120:121], s[10:11] op_sel_hi:[1,1,0]
	v_pk_fma_f32 v[122:123], v[108:109], v[122:123], s[10:11] op_sel_hi:[1,1,0]
	v_pk_fma_f32 v[124:125], v[112:113], v[124:125], s[10:11] op_sel_hi:[1,1,0]
	v_pk_fma_f32 v[118:119], v[116:117], v[118:119], s[10:11] op_sel_hi:[1,1,0]
	s_mov_b32 s10, 0x3d530477
	v_cndmask_b32_e64 v36, v20, v36, s[40:41]
	v_pk_fma_f32 v[120:121], v[64:65], v[120:121], s[10:11] op_sel_hi:[1,1,0]
	v_pk_fma_f32 v[122:123], v[108:109], v[122:123], s[10:11] op_sel_hi:[1,1,0]
	v_pk_fma_f32 v[124:125], v[112:113], v[124:125], s[10:11] op_sel_hi:[1,1,0]
	v_pk_fma_f32 v[118:119], v[116:117], v[118:119], s[10:11] op_sel_hi:[1,1,0]
	s_mov_b32 s10, 0xffffffffbd8ff74d
	v_cndmask_b32_e64 v37, v21, v37, s[40:41]
	v_pk_fma_f32 v[120:121], v[64:65], v[120:121], s[10:11] op_sel_hi:[1,1,0]
	v_pk_fma_f32 v[122:123], v[108:109], v[122:123], s[10:11] op_sel_hi:[1,1,0]
	v_pk_fma_f32 v[124:125], v[112:113], v[124:125], s[10:11] op_sel_hi:[1,1,0]
	v_pk_fma_f32 v[118:119], v[116:117], v[118:119], s[10:11] op_sel_hi:[1,1,0]
	s_mov_b32 s10, 0x3e10c1ad
	v_mov_b32_dpp v36, v36 row_ror:1 row_mask:0xf bank_mask:0xf bound_ctrl:1
	v_pk_fma_f32 v[64:65], v[64:65], v[120:121], s[10:11] op_sel_hi:[1,1,0]
	v_pk_fma_f32 v[108:109], v[108:109], v[122:123], s[10:11] op_sel_hi:[1,1,0]
	v_pk_fma_f32 v[62:63], v[62:63], v[64:65], 0.5 op_sel_hi:[1,1,0]
	v_pk_fma_f32 v[112:113], v[112:113], v[124:125], s[10:11] op_sel_hi:[1,1,0]
	v_pk_mul_f32 v[56:57], v[56:57], v[62:63]
	v_pk_fma_f32 v[62:63], v[66:67], v[108:109], 0.5 op_sel_hi:[1,1,0]
	v_pk_fma_f32 v[116:117], v[116:117], v[118:119], s[10:11] op_sel_hi:[1,1,0]
	v_pk_mul_f32 v[58:59], v[58:59], v[62:63]
	v_pk_fma_f32 v[62:63], v[110:111], v[112:113], 0.5 op_sel_hi:[1,1,0]
	v_mul_f32_e32 v48, v48, v56
	v_pk_mul_f32 v[52:53], v[52:53], v[62:63]
	v_pk_fma_f32 v[62:63], v[114:115], v[116:117], 0.5 op_sel_hi:[1,1,0]
	v_mul_f32_e32 v49, v49, v57
	v_pk_mul_f32 v[54:55], v[54:55], v[62:63]
	v_mul_f32_e32 v52, v44, v52
	v_cvt_pk_bf16_f32 v44, v48, v49
	v_mad_i64_i32 v[48:49], s[10:11], v126, s3, v[60:61]
	v_mul_f32_e32 v50, v50, v58
	v_mul_f32_e32 v51, v51, v59
	v_mul_f32_e32 v53, v45, v53
	v_mul_f32_e32 v47, v47, v55
	v_cvt_pk_bf16_f32 v45, v50, v51
	v_lshl_add_u64 v[48:49], v[48:49], 0, v[156:157]
	v_mul_f32_e32 v54, v46, v54
	v_cvt_pk_bf16_f32 v46, v52, v53
	v_cvt_pk_bf16_f32 v47, v54, v47
	global_store_dwordx4 v[48:49], v[44:47], off nt
	v_mov_b32_dpp v37, v37 row_ror:1 row_mask:0xf bank_mask:0xf bound_ctrl:1
	v_cndmask_b32_e64 v38, v22, v38, s[40:41]
	v_cndmask_b32_e64 v44, v24, v16, s[38:39]
	v_cndmask_b32_e64 v45, v25, v17, s[38:39]
	v_cndmask_b32_e64 v39, v23, v39, s[40:41]
	v_mov_b32_dpp v44, v44 row_ror:15 row_mask:0xf bank_mask:0xf bound_ctrl:1
	v_mov_b32_dpp v45, v45 row_ror:15 row_mask:0xf bank_mask:0xf bound_ctrl:1
	v_pk_fma_f32 v[44:45], v[100:101], v[44:45], v[104:105]
	v_mov_b32_dpp v38, v38 row_ror:1 row_mask:0xf bank_mask:0xf bound_ctrl:1
	v_pk_fma_f32 v[44:45], v[96:97], v[24:25], v[44:45]
	v_mov_b32_dpp v39, v39 row_ror:1 row_mask:0xf bank_mask:0xf bound_ctrl:1
	v_pk_fma_f32 v[40:41], v[92:93], v[40:41], v[44:45]
	v_cndmask_b32_e64 v44, v26, v18, s[38:39]
	v_cndmask_b32_e64 v45, v27, v19, s[38:39]
	s_mov_b32 s10, 0x3a40c646
	s_mov_b32 s18, 0xffffffffbadbc5c1
	v_add_u32_e32 v110, 0xa0, v201
	v_mov_b32_dpp v44, v44 row_ror:15 row_mask:0xf bank_mask:0xf bound_ctrl:1
	v_mov_b32_dpp v45, v45 row_ror:15 row_mask:0xf bank_mask:0xf bound_ctrl:1
	v_pk_fma_f32 v[44:45], v[102:103], v[44:45], v[106:107]
	v_mov_b64_e32 v[62:63], s[18:19]
	v_pk_fma_f32 v[44:45], v[98:99], v[26:27], v[44:45]
	v_cndmask_b32_e64 v24, v16, v24, s[40:41]
	v_pk_fma_f32 v[42:43], v[94:95], v[42:43], v[44:45]
	v_cndmask_b32_e64 v44, v20, v12, s[38:39]
	v_cndmask_b32_e64 v45, v21, v13, s[38:39]
	v_med3_f32 v48, v42, s25, v248
	v_mov_b32_dpp v44, v44 row_ror:15 row_mask:0xf bank_mask:0xf bound_ctrl:1
	v_mov_b32_dpp v45, v45 row_ror:15 row_mask:0xf bank_mask:0xf bound_ctrl:1
	v_pk_fma_f32 v[44:45], v[84:85], v[44:45], v[88:89]
	v_med3_f32 v49, v43, s25, v248
	v_pk_fma_f32 v[44:45], v[76:77], v[20:21], v[44:45]
	v_pk_mul_f32 v[50:51], v[48:49], v[48:49]
	v_pk_fma_f32 v[36:37], v[72:73], v[36:37], v[44:45]
	v_cndmask_b32_e64 v44, v22, v14, s[38:39]
	v_cndmask_b32_e64 v45, v23, v15, s[38:39]
	v_med3_f32 v52, v36, s25, v248
; __device__ __forceinline__ void gelu4(const f32x2 (&v)[4], f32x2 (&o)[4]) {
;     ...
;     for (int p = 0; p < 4; ++p) { c[p].x = __builtin_amdgcn_fmed3f(v[p].x, -5.0f, 5.0f); c[p].y = __builtin_amdgcn_fmed3f(v[p].y, -5.0f, 5.0f); w[p] = (c[p] * c[p]) * 0.08f + (-1.0f); }
;     { const float ka = kc<0x3a40c646u>(), kb = kc<0xbadbc5c1u>();
; #pragma unroll
;       for (int p = 0; p < 4; ++p) q[p] = w[p] * ka + kb; }
;     { const float kk = kc<0x3ab42bcbu>();
; #pragma unroll
;       for (int p = 0; p < 4; ++p) q[p] = q[p] * w[p] + kk; }
;     { const float kk = kc<0xbb259aa1u>();
; #pragma unroll
;       for (int p = 0; p < 4; ++p) q[p] = q[p] * w[p] + kk; }
;     { const float kk = kc<0x3bddb9bfu>();
; #pragma unroll
;       for (int p = 0; p < 4; ++p) q[p] = q[p] * w[p] + kk; }
;     { const float kk = kc<0xbc394185u>();
; #pragma unroll
;       for (int p = 0; p < 4; ++p) q[p] = q[p] * w[p] + kk; }
;     { const float kk = kc<0x3c85018cu>();
; #pragma unroll
;       for (int p = 0; p < 4; ++p) q[p] = q[p] * w[p] + kk; }
;     { const float kk = kc<0xbcbe2975u>();
; #pragma unroll
;       for (int p = 0; p < 4; ++p) q[p] = q[p] * w[p] + kk; }
;     { const float kk = kc<0x3d00edc6u>();
; #pragma unroll
;       for (int p = 0; p < 4; ++p) q[p] = q[p] * w[p] + kk; }
;     { const float kk = kc<0xbd25b03eu>();
; #pragma unroll
;       for (int p = 0; p < 4; ++p) q[p] = q[p] * w[p] + kk; }
;     { const float kk = kc<0x3d530477u>();
; #pragma unroll
;       for (int p = 0; p < 4; ++p) q[p] = q[p] * w[p] + kk; }
;     { const float kk = kc<0xbd8ff74du>();
; #pragma unroll
;       for (int p = 0; p < 4; ++p) q[p] = q[p] * w[p] + kk; }
;     { const float kk = kc<0x3e10c1adu>();
; #pragma unroll
;       for (int p = 0; p < 4; ++p) q[p] = q[p] * w[p] + kk; }
;     __device__ __forceinline__ void operator()(const f32x4 (&acc)[2][2][4][2], const Unit& u, int wr, int wc, int fr, int fq) const {
;     ...
;                         const float g = acc[ai][1][m][n][j];
;                         const float tp = l15 ? ((m > 0) ? acc[ai][1][m > 0 ? m - 1 : 0][n][j] : xp[n][j]) : g;
;                         const float tn = l0  ? ((m < 3) ? acc[ai][1][m < 3 ? m + 1 : 3][n][j] : xn[n][j]) : g;
;                         const float gp = ror1(tp), gn = ror15(tn);
;                         cv[4 * n + j] = fmaf(w0[n][j], gp, fmaf(w1[n][j], g, fmaf(w2[n][j], gn, bb[n][j])));
	v_mov_b32_dpp v44, v44 row_ror:15 row_mask:0xf bank_mask:0xf bound_ctrl:1
	v_mov_b32_dpp v45, v45 row_ror:15 row_mask:0xf bank_mask:0xf bound_ctrl:1
	v_pk_fma_f32 v[44:45], v[86:87], v[44:45], v[90:91]
	v_med3_f32 v53, v37, s25, v248
	v_pk_fma_f32 v[44:45], v[78:79], v[22:23], v[44:45]
	v_pk_mul_f32 v[54:55], v[52:53], v[52:53]
	v_pk_fma_f32 v[38:39], v[74:75], v[38:39], v[44:45]
	v_med3_f32 v44, v40, s25, v248
	v_med3_f32 v45, v41, s25, v248
	v_pk_mul_f32 v[46:47], v[44:45], v[44:45]
	v_med3_f32 v56, v38, s25, v248
	v_med3_f32 v57, v39, s25, v248
	v_pk_fma_f32 v[46:47], v[46:47], s[14:15], -1.0 op_sel_hi:[1,0,0]
	v_pk_mul_f32 v[58:59], v[56:57], v[56:57]
	v_pk_fma_f32 v[50:51], v[50:51], s[14:15], -1.0 op_sel_hi:[1,0,0]
	v_pk_fma_f32 v[54:55], v[54:55], s[14:15], -1.0 op_sel_hi:[1,0,0]
	v_pk_fma_f32 v[58:59], v[58:59], s[14:15], -1.0 op_sel_hi:[1,0,0]
	v_pk_fma_f32 v[64:65], v[46:47], s[10:11], v[62:63] op_sel_hi:[1,0,0]
	v_pk_fma_f32 v[66:67], v[50:51], s[10:11], v[62:63] op_sel_hi:[1,0,0]
	v_pk_fma_f32 v[108:109], s[10:11], v[54:55], v[62:63] op_sel_hi:[0,1,0]
	v_pk_fma_f32 v[62:63], s[10:11], v[58:59], v[62:63] op_sel_hi:[0,1,0]
	s_mov_b32 s10, 0x3ab42bcb
	v_cndmask_b32_e64 v25, v17, v25, s[40:41]
	v_pk_fma_f32 v[64:65], v[46:47], v[64:65], s[10:11] op_sel_hi:[1,1,0]
	v_pk_fma_f32 v[66:67], v[50:51], v[66:67], s[10:11] op_sel_hi:[1,1,0]
	v_pk_fma_f32 v[108:109], v[54:55], v[108:109], s[10:11] op_sel_hi:[1,1,0]
	v_pk_fma_f32 v[62:63], v[58:59], v[62:63], s[10:11] op_sel_hi:[1,1,0]
	s_mov_b32 s10, 0xffffffffbb259aa1
	v_mov_b32_dpp v24, v24 row_ror:1 row_mask:0xf bank_mask:0xf bound_ctrl:1
	v_pk_fma_f32 v[64:65], v[46:47], v[64:65], s[10:11] op_sel_hi:[1,1,0]
	v_pk_fma_f32 v[66:67], v[50:51], v[66:67], s[10:11] op_sel_hi:[1,1,0]
	v_pk_fma_f32 v[108:109], v[54:55], v[108:109], s[10:11] op_sel_hi:[1,1,0]
	v_pk_fma_f32 v[62:63], v[58:59], v[62:63], s[10:11] op_sel_hi:[1,1,0]
	s_mov_b32 s10, 0x3bddb9bf
	v_mov_b32_dpp v25, v25 row_ror:1 row_mask:0xf bank_mask:0xf bound_ctrl:1
	v_pk_fma_f32 v[64:65], v[46:47], v[64:65], s[10:11] op_sel_hi:[1,1,0]
	v_pk_fma_f32 v[66:67], v[50:51], v[66:67], s[10:11] op_sel_hi:[1,1,0]
	v_pk_fma_f32 v[108:109], v[54:55], v[108:109], s[10:11] op_sel_hi:[1,1,0]
	v_pk_fma_f32 v[62:63], v[58:59], v[62:63], s[10:11] op_sel_hi:[1,1,0]
	s_mov_b32 s10, 0xffffffffbc394185
	v_cndmask_b32_e64 v26, v18, v26, s[40:41]
	v_pk_fma_f32 v[64:65], v[46:47], v[64:65], s[10:11] op_sel_hi:[1,1,0]
	v_pk_fma_f32 v[66:67], v[50:51], v[66:67], s[10:11] op_sel_hi:[1,1,0]
	v_pk_fma_f32 v[108:109], v[54:55], v[108:109], s[10:11] op_sel_hi:[1,1,0]
	v_pk_fma_f32 v[62:63], v[58:59], v[62:63], s[10:11] op_sel_hi:[1,1,0]
	s_mov_b32 s10, 0x3c85018c
	v_cndmask_b32_e64 v27, v19, v27, s[40:41]
	v_pk_fma_f32 v[64:65], v[46:47], v[64:65], s[10:11] op_sel_hi:[1,1,0]
	v_pk_fma_f32 v[66:67], v[50:51], v[66:67], s[10:11] op_sel_hi:[1,1,0]
	v_pk_fma_f32 v[108:109], v[54:55], v[108:109], s[10:11] op_sel_hi:[1,1,0]
	v_pk_fma_f32 v[62:63], v[58:59], v[62:63], s[10:11] op_sel_hi:[1,1,0]
	s_mov_b32 s10, 0xffffffffbcbe2975
	v_mov_b32_dpp v26, v26 row_ror:1 row_mask:0xf bank_mask:0xf bound_ctrl:1
	v_pk_fma_f32 v[64:65], v[46:47], v[64:65], s[10:11] op_sel_hi:[1,1,0]
	v_pk_fma_f32 v[66:67], v[50:51], v[66:67], s[10:11] op_sel_hi:[1,1,0]
	v_pk_fma_f32 v[108:109], v[54:55], v[108:109], s[10:11] op_sel_hi:[1,1,0]
	v_pk_fma_f32 v[62:63], v[58:59], v[62:63], s[10:11] op_sel_hi:[1,1,0]
	s_mov_b32 s10, 0x3d00edc6
	v_mov_b32_dpp v27, v27 row_ror:1 row_mask:0xf bank_mask:0xf bound_ctrl:1
	v_pk_fma_f32 v[64:65], v[46:47], v[64:65], s[10:11] op_sel_hi:[1,1,0]
	v_pk_fma_f32 v[66:67], v[50:51], v[66:67], s[10:11] op_sel_hi:[1,1,0]
	v_pk_fma_f32 v[108:109], v[54:55], v[108:109], s[10:11] op_sel_hi:[1,1,0]
	v_pk_fma_f32 v[62:63], v[58:59], v[62:63], s[10:11] op_sel_hi:[1,1,0]
	s_mov_b32 s10, 0xffffffffbd25b03e
	v_cndmask_b32_e64 v20, v12, v20, s[40:41]
	v_pk_fma_f32 v[64:65], v[46:47], v[64:65], s[10:11] op_sel_hi:[1,1,0]
	v_pk_fma_f32 v[66:67], v[50:51], v[66:67], s[10:11] op_sel_hi:[1,1,0]
	v_pk_fma_f32 v[108:109], v[54:55], v[108:109], s[10:11] op_sel_hi:[1,1,0]
	v_pk_fma_f32 v[62:63], v[58:59], v[62:63], s[10:11] op_sel_hi:[1,1,0]
	s_mov_b32 s10, 0x3d530477
	v_cndmask_b32_e64 v21, v13, v21, s[40:41]
	v_pk_fma_f32 v[64:65], v[46:47], v[64:65], s[10:11] op_sel_hi:[1,1,0]
	v_pk_fma_f32 v[66:67], v[50:51], v[66:67], s[10:11] op_sel_hi:[1,1,0]
	v_pk_fma_f32 v[108:109], v[54:55], v[108:109], s[10:11] op_sel_hi:[1,1,0]
	v_pk_fma_f32 v[62:63], v[58:59], v[62:63], s[10:11] op_sel_hi:[1,1,0]
	s_mov_b32 s10, 0xffffffffbd8ff74d
	v_mov_b32_dpp v20, v20 row_ror:1 row_mask:0xf bank_mask:0xf bound_ctrl:1
	v_pk_fma_f32 v[64:65], v[46:47], v[64:65], s[10:11] op_sel_hi:[1,1,0]
	v_pk_fma_f32 v[66:67], v[50:51], v[66:67], s[10:11] op_sel_hi:[1,1,0]
	v_pk_fma_f32 v[108:109], v[54:55], v[108:109], s[10:11] op_sel_hi:[1,1,0]
	v_pk_fma_f32 v[62:63], v[58:59], v[62:63], s[10:11] op_sel_hi:[1,1,0]
	s_mov_b32 s10, 0x3e10c1ad
	v_mov_b32_dpp v21, v21 row_ror:1 row_mask:0xf bank_mask:0xf bound_ctrl:1
	v_pk_fma_f32 v[46:47], v[46:47], v[64:65], s[10:11] op_sel_hi:[1,1,0]
	v_pk_fma_f32 v[50:51], v[50:51], v[66:67], s[10:11] op_sel_hi:[1,1,0]
	v_pk_fma_f32 v[44:45], v[44:45], v[46:47], 0.5 op_sel_hi:[1,1,0]
	v_pk_fma_f32 v[54:55], v[54:55], v[108:109], s[10:11] op_sel_hi:[1,1,0]
	v_pk_mul_f32 v[40:41], v[40:41], v[44:45]
	v_pk_fma_f32 v[44:45], v[48:49], v[50:51], 0.5 op_sel_hi:[1,1,0]
	v_pk_fma_f32 v[58:59], v[58:59], v[62:63], s[10:11] op_sel_hi:[1,1,0]
	v_pk_mul_f32 v[42:43], v[42:43], v[44:45]
	v_pk_fma_f32 v[44:45], v[52:53], v[54:55], 0.5 op_sel_hi:[1,1,0]
	v_mul_f32_e32 v32, v32, v40
; __device__ __forceinline__ unsigned cvt_pk_bf16(float lo, float hi) { unsigned r; asm volatile("v_cvt_pk_bf16_f32 %0, %1, %2" : "=v"(r) : "v"(lo), "v"(hi)); return r; }
;     static __device__ __forceinline__ float ror1(float v)  { return __builtin_bit_cast(float, __builtin_amdgcn_update_dpp(0, __builtin_bit_cast(int, v), 0x121, 0xf, 0xf, true)); }
;     static __device__ __forceinline__ float ror15(float v) { return __builtin_bit_cast(float, __builtin_amdgcn_update_dpp(0, __builtin_bit_cast(int, v), 0x12f, 0xf, 0xf, true)); }
; __device__ __forceinline__ void gelu4(const f32x2 (&v)[4], f32x2 (&o)[4]) {
;     ...
;     for (int p = 0; p < 4; ++p) o[p] = v[p] * (q[p] * c[p] + 0.5f);
;     __device__ __forceinline__ void operator()(const f32x4 (&acc)[2][2][4][2], const Unit& u, int wr, int wc, int fr, int fq) const {
;     ...
;                         const float g = acc[ai][1][m][n][j];
;                         const float tp = l15 ? ((m > 0) ? acc[ai][1][m > 0 ? m - 1 : 0][n][j] : xp[n][j]) : g;
;                         const float tn = l0  ? ((m < 3) ? acc[ai][1][m < 3 ? m + 1 : 3][n][j] : xn[n][j]) : g;
;                         const float gp = ror1(tp), gn = ror15(tn);
;                         cv[4 * n + j] = fmaf(w0[n][j], gp, fmaf(w1[n][j], g, fmaf(w2[n][j], gn, bb[n][j])));
;                     }
;                 const int tr = ai * HALF + wr * 64 + m * 16 + fr;
;                 if (tr == 0 || tr == 255) { float* sb = SB + ((size_t)(u.pm * 2 + (tr ? 1 : 0)) * 3) * dff + ch0;
; #pragma unroll
;                     for (int n = 0; n < 2; ++n) { *(f32x4*)(sb + 4 * n) = (f32x4){cv[4 * n], cv[4 * n + 1], cv[4 * n + 2], cv[4 * n + 3]}; *(f32x4*)(sb + dff + 4 * n) = acc[ai][0][m][n]; *(f32x4*)(sb + 2 * dff + 4 * n) = acc[ai][1][m][n]; } }
;                 f32x2 gv[4], go[4]; float a[8];
; #pragma unroll
;                 for (int p = 0; p < 4; ++p) gv[p] = (f32x2){cv[2 * p], cv[2 * p + 1]};
;                 gelu4(gv, go);
; #pragma unroll
;                 for (int e = 0; e < 8; e += 2) { a[e] = go[e >> 1].x * acc[ai][0][m][e >> 2][e & 3]; a[e + 1] = go[e >> 1].y * acc[ai][0][m][(e + 1) >> 2][(e + 1) & 3]; }
;                 ow.x = cvt_pk_bf16(a[0], a[1]); ow.y = cvt_pk_bf16(a[2], a[3]); ow.z = cvt_pk_bf16(a[4], a[5]); ow.w = cvt_pk_bf16(a[6], a[7]);
;                 *(u32x4*)(ACT + (size_t)row * ldc + ch0) = ow;
	v_pk_mul_f32 v[36:37], v[36:37], v[44:45]
	v_pk_fma_f32 v[44:45], v[56:57], v[58:59], 0.5 op_sel_hi:[1,1,0]
	v_mul_f32_e32 v33, v33, v41
	v_pk_mul_f32 v[38:39], v[38:39], v[44:45]
	v_mul_f32_e32 v36, v28, v36
	v_cvt_pk_bf16_f32 v28, v32, v33
	v_mad_i64_i32 v[32:33], s[10:11], v110, s3, v[60:61]
	v_mul_f32_e32 v34, v34, v42
	v_mul_f32_e32 v35, v35, v43
	v_mul_f32_e32 v37, v29, v37
	v_mul_f32_e32 v31, v31, v39
	v_cvt_pk_bf16_f32 v29, v34, v35
	v_lshl_add_u64 v[32:33], v[32:33], 0, v[156:157]
	v_mul_f32_e32 v38, v30, v38
	v_cvt_pk_bf16_f32 v30, v36, v37
	v_cvt_pk_bf16_f32 v31, v38, v31
	global_store_dwordx4 v[32:33], v[28:31], off nt
	v_cndmask_b32_e64 v22, v14, v22, s[40:41]
	v_cndmask_b32_e64 v23, v15, v23, s[40:41]
	v_cndmask_b32_e64 v28, v16, v80, s[38:39]
	v_cndmask_b32_e64 v29, v17, v81, s[38:39]
	v_mov_b32_dpp v22, v22 row_ror:1 row_mask:0xf bank_mask:0xf bound_ctrl:1
	v_mov_b32_dpp v28, v28 row_ror:15 row_mask:0xf bank_mask:0xf bound_ctrl:1
	v_mov_b32_dpp v29, v29 row_ror:15 row_mask:0xf bank_mask:0xf bound_ctrl:1
	v_pk_fma_f32 v[28:29], v[100:101], v[28:29], v[104:105]
	v_mov_b32_dpp v23, v23 row_ror:1 row_mask:0xf bank_mask:0xf bound_ctrl:1
	v_pk_fma_f32 v[28:29], v[96:97], v[16:17], v[28:29]
	s_nop 0
	v_pk_fma_f32 v[24:25], v[92:93], v[24:25], v[28:29]
	v_cndmask_b32_e64 v28, v18, v82, s[38:39]
	v_cndmask_b32_e64 v29, v19, v83, s[38:39]
	s_nop 0
	v_mov_b32_dpp v28, v28 row_ror:15 row_mask:0xf bank_mask:0xf bound_ctrl:1
	v_mov_b32_dpp v29, v29 row_ror:15 row_mask:0xf bank_mask:0xf bound_ctrl:1
	v_pk_fma_f32 v[28:29], v[102:103], v[28:29], v[106:107]
	s_nop 0
	v_pk_fma_f32 v[28:29], v[98:99], v[18:19], v[28:29]
	s_nop 0
	v_pk_fma_f32 v[26:27], v[94:95], v[26:27], v[28:29]
	v_cndmask_b32_e64 v28, v12, v68, s[38:39]
	v_cndmask_b32_e64 v29, v13, v69, s[38:39]
	s_nop 0
	v_mov_b32_dpp v28, v28 row_ror:15 row_mask:0xf bank_mask:0xf bound_ctrl:1
	v_mov_b32_dpp v29, v29 row_ror:15 row_mask:0xf bank_mask:0xf bound_ctrl:1
	v_pk_fma_f32 v[28:29], v[84:85], v[28:29], v[88:89]
	s_nop 0
	v_pk_fma_f32 v[28:29], v[76:77], v[12:13], v[28:29]
	s_nop 0
	v_pk_fma_f32 v[20:21], v[72:73], v[20:21], v[28:29]
	v_cndmask_b32_e64 v28, v14, v70, s[38:39]
	v_cndmask_b32_e64 v29, v15, v71, s[38:39]
	s_nop 0
	v_mov_b32_dpp v28, v28 row_ror:15 row_mask:0xf bank_mask:0xf bound_ctrl:1
	v_mov_b32_dpp v29, v29 row_ror:15 row_mask:0xf bank_mask:0xf bound_ctrl:1
	v_pk_fma_f32 v[28:29], v[86:87], v[28:29], v[90:91]
	s_nop 0
	v_pk_fma_f32 v[28:29], v[78:79], v[14:15], v[28:29]
	s_nop 0
	v_pk_fma_f32 v[22:23], v[74:75], v[22:23], v[28:29]
	s_and_saveexec_b64 s[10:11], s[48:49]
	s_cbranch_execz .LBB0_1261
	s_or_b32 s8, s8, 1
	s_mul_hi_i32 s13, s8, 0x10800
	s_mul_i32 s8, s8, 0x10800
	s_add_u32 s18, s90, s8
	s_addc_u32 s19, s91, s13
	v_lshl_add_u64 v[28:29], v[190:191], 2, s[18:19]
	v_add_co_u32_e32 v30, vcc, 0x5000, v28
	global_store_dwordx4 v[28:29], v[24:27], off
	s_nop 0
	v_addc_co_u32_e32 v31, vcc, 0, v29, vcc
	v_add_co_u32_e32 v32, vcc, 0xb000, v28
	global_store_dwordx4 v[30:31], v[8:11], off offset:2048
	s_nop 0
	v_addc_co_u32_e32 v33, vcc, 0, v29, vcc
	global_store_dwordx4 v[32:33], v[16:19], off
	global_store_dwordx4 v[28:29], v[20:23], off offset:16
	global_store_dwordx4 v[30:31], v[4:7], off offset:2064
	global_store_dwordx4 v[32:33], v[12:15], off offset:16
; __device__ __forceinline__ void gelu4(const f32x2 (&v)[4], f32x2 (&o)[4]) {
;     ...
;     for (int p = 0; p < 4; ++p) { c[p].x = __builtin_amdgcn_fmed3f(v[p].x, -5.0f, 5.0f); c[p].y = __builtin_amdgcn_fmed3f(v[p].y, -5.0f, 5.0f); w[p] = (c[p] * c[p]) * 0.08f + (-1.0f); }
;     { const float ka = kc<0x3a40c646u>(), kb = kc<0xbadbc5c1u>();
; #pragma unroll
;       for (int p = 0; p < 4; ++p) q[p] = w[p] * ka + kb; }
;     { const float kk = kc<0x3ab42bcbu>();
; #pragma unroll
;       for (int p = 0; p < 4; ++p) q[p] = q[p] * w[p] + kk; }
;     { const float kk = kc<0xbb259aa1u>();
; #pragma unroll
;       for (int p = 0; p < 4; ++p) q[p] = q[p] * w[p] + kk; }
;     { const float kk = kc<0x3bddb9bfu>();
; #pragma unroll
;       for (int p = 0; p < 4; ++p) q[p] = q[p] * w[p] + kk; }
;     { const float kk = kc<0xbc394185u>();
; #pragma unroll
;       for (int p = 0; p < 4; ++p) q[p] = q[p] * w[p] + kk; }
;     { const float kk = kc<0x3c85018cu>();
; #pragma unroll
;       for (int p = 0; p < 4; ++p) q[p] = q[p] * w[p] + kk; }
;     { const float kk = kc<0xbcbe2975u>();
; #pragma unroll
;       for (int p = 0; p < 4; ++p) q[p] = q[p] * w[p] + kk; }
;     { const float kk = kc<0x3d00edc6u>();
; #pragma unroll
;       for (int p = 0; p < 4; ++p) q[p] = q[p] * w[p] + kk; }
;     { const float kk = kc<0xbd25b03eu>();
; #pragma unroll
;       for (int p = 0; p < 4; ++p) q[p] = q[p] * w[p] + kk; }
;     { const float kk = kc<0x3d530477u>();
; #pragma unroll
;       for (int p = 0; p < 4; ++p) q[p] = q[p] * w[p] + kk; }
;     { const float kk = kc<0xbd8ff74du>();
; #pragma unroll
;       for (int p = 0; p < 4; ++p) q[p] = q[p] * w[p] + kk; }
;     { const float kk = kc<0x3e10c1adu>();
; #pragma unroll
;       for (int p = 0; p < 4; ++p) q[p] = q[p] * w[p] + kk; }
; #pragma unroll
;     for (int p = 0; p < 4; ++p) o[p] = v[p] * (q[p] * c[p] + 0.5f);
;     __device__ __forceinline__ void operator()(const f32x4 (&acc)[2][2][4][2], const Unit& u, int wr, int wc, int fr, int fq) const {
;     ...
;                 f32x2 gv[4], go[4]; float a[8];
; #pragma unroll
;                 for (int p = 0; p < 4; ++p) gv[p] = (f32x2){cv[2 * p], cv[2 * p + 1]};
;                 gelu4(gv, go);
; #pragma unroll
;                 for (int e = 0; e < 8; e += 2) { a[e] = go[e >> 1].x * acc[ai][0][m][e >> 2][e & 3]; a[e + 1] = go[e >> 1].y * acc[ai][0][m][(e + 1) >> 2][(e + 1) & 3]; }
.LBB0_1261:
	s_or_b64 exec, exec, s[10:11]
	s_nop 0
	v_med3_f32 v12, v24, s25, v248
	v_med3_f32 v13, v25, s25, v248
	v_pk_mul_f32 v[14:15], v[12:13], v[12:13]
	v_med3_f32 v16, v26, s25, v248
	v_med3_f32 v17, v27, s25, v248
	v_med3_f32 v28, v20, s25, v248
	v_med3_f32 v29, v21, s25, v248
	v_med3_f32 v32, v22, s25, v248
	v_med3_f32 v33, v23, s25, v248
	v_pk_fma_f32 v[14:15], v[14:15], s[14:15], -1.0 op_sel_hi:[1,0,0]
	v_pk_mul_f32 v[18:19], v[16:17], v[16:17]
	v_pk_mul_f32 v[30:31], v[28:29], v[28:29]
	v_pk_mul_f32 v[34:35], v[32:33], v[32:33]
	s_mov_b32 s8, 0x3a40c646
	s_mov_b32 s10, 0xffffffffbadbc5c1
	v_pk_fma_f32 v[18:19], v[18:19], s[14:15], -1.0 op_sel_hi:[1,0,0]
	v_mov_b64_e32 v[36:37], s[10:11]
	v_pk_fma_f32 v[30:31], v[30:31], s[14:15], -1.0 op_sel_hi:[1,0,0]
	v_pk_fma_f32 v[34:35], v[34:35], s[14:15], -1.0 op_sel_hi:[1,0,0]
	v_pk_fma_f32 v[38:39], v[14:15], s[8:9], v[36:37] op_sel_hi:[1,0,0]
	v_pk_fma_f32 v[40:41], v[18:19], s[8:9], v[36:37] op_sel_hi:[1,0,0]
	v_pk_fma_f32 v[42:43], v[30:31], s[8:9], v[36:37] op_sel_hi:[1,0,0]
	v_pk_fma_f32 v[36:37], v[34:35], s[8:9], v[36:37] op_sel_hi:[1,0,0]
	s_mov_b32 s8, 0x3ab42bcb
	v_add_u32_e32 v44, 0xb0, v201
	v_pk_fma_f32 v[38:39], v[14:15], v[38:39], s[8:9] op_sel_hi:[1,1,0]
	v_pk_fma_f32 v[40:41], v[18:19], v[40:41], s[8:9] op_sel_hi:[1,1,0]
	v_pk_fma_f32 v[42:43], v[30:31], v[42:43], s[8:9] op_sel_hi:[1,1,0]
	v_pk_fma_f32 v[36:37], v[34:35], v[36:37], s[8:9] op_sel_hi:[1,1,0]
	s_mov_b32 s8, 0xffffffffbb259aa1
	s_andn2_b64 vcc, exec, s[50:51]
	v_pk_fma_f32 v[38:39], v[14:15], v[38:39], s[8:9] op_sel_hi:[1,1,0]
	v_pk_fma_f32 v[40:41], v[18:19], v[40:41], s[8:9] op_sel_hi:[1,1,0]
	v_pk_fma_f32 v[42:43], v[30:31], v[42:43], s[8:9] op_sel_hi:[1,1,0]
	v_pk_fma_f32 v[36:37], v[34:35], v[36:37], s[8:9] op_sel_hi:[1,1,0]
	s_mov_b32 s8, 0x3bddb9bf
	s_nop 0
	v_pk_fma_f32 v[38:39], v[14:15], v[38:39], s[8:9] op_sel_hi:[1,1,0]
	v_pk_fma_f32 v[40:41], v[18:19], v[40:41], s[8:9] op_sel_hi:[1,1,0]
	v_pk_fma_f32 v[42:43], v[30:31], v[42:43], s[8:9] op_sel_hi:[1,1,0]
	v_pk_fma_f32 v[36:37], v[34:35], v[36:37], s[8:9] op_sel_hi:[1,1,0]
	s_mov_b32 s8, 0xffffffffbc394185
	s_nop 0
	v_pk_fma_f32 v[38:39], v[14:15], v[38:39], s[8:9] op_sel_hi:[1,1,0]
	v_pk_fma_f32 v[40:41], v[18:19], v[40:41], s[8:9] op_sel_hi:[1,1,0]
	v_pk_fma_f32 v[42:43], v[30:31], v[42:43], s[8:9] op_sel_hi:[1,1,0]
	v_pk_fma_f32 v[36:37], v[34:35], v[36:37], s[8:9] op_sel_hi:[1,1,0]
	s_mov_b32 s8, 0x3c85018c
	s_nop 0
	v_pk_fma_f32 v[38:39], v[14:15], v[38:39], s[8:9] op_sel_hi:[1,1,0]
	v_pk_fma_f32 v[40:41], v[18:19], v[40:41], s[8:9] op_sel_hi:[1,1,0]
	v_pk_fma_f32 v[42:43], v[30:31], v[42:43], s[8:9] op_sel_hi:[1,1,0]
	v_pk_fma_f32 v[36:37], v[34:35], v[36:37], s[8:9] op_sel_hi:[1,1,0]
	s_mov_b32 s8, 0xffffffffbcbe2975
	s_nop 0
	v_pk_fma_f32 v[38:39], v[14:15], v[38:39], s[8:9] op_sel_hi:[1,1,0]
	v_pk_fma_f32 v[40:41], v[18:19], v[40:41], s[8:9] op_sel_hi:[1,1,0]
	v_pk_fma_f32 v[42:43], v[30:31], v[42:43], s[8:9] op_sel_hi:[1,1,0]
	v_pk_fma_f32 v[36:37], v[34:35], v[36:37], s[8:9] op_sel_hi:[1,1,0]
	s_mov_b32 s8, 0x3d00edc6
	s_nop 0
	v_pk_fma_f32 v[38:39], v[14:15], v[38:39], s[8:9] op_sel_hi:[1,1,0]
	v_pk_fma_f32 v[40:41], v[18:19], v[40:41], s[8:9] op_sel_hi:[1,1,0]
	v_pk_fma_f32 v[42:43], v[30:31], v[42:43], s[8:9] op_sel_hi:[1,1,0]
	v_pk_fma_f32 v[36:37], v[34:35], v[36:37], s[8:9] op_sel_hi:[1,1,0]
	s_mov_b32 s8, 0xffffffffbd25b03e
	s_nop 0
	v_pk_fma_f32 v[38:39], v[14:15], v[38:39], s[8:9] op_sel_hi:[1,1,0]
	v_pk_fma_f32 v[40:41], v[18:19], v[40:41], s[8:9] op_sel_hi:[1,1,0]
	v_pk_fma_f32 v[42:43], v[30:31], v[42:43], s[8:9] op_sel_hi:[1,1,0]
	v_pk_fma_f32 v[36:37], v[34:35], v[36:37], s[8:9] op_sel_hi:[1,1,0]
	s_mov_b32 s8, 0x3d530477
	s_nop 0
	v_pk_fma_f32 v[38:39], v[14:15], v[38:39], s[8:9] op_sel_hi:[1,1,0]
	v_pk_fma_f32 v[40:41], v[18:19], v[40:41], s[8:9] op_sel_hi:[1,1,0]
	v_pk_fma_f32 v[42:43], v[30:31], v[42:43], s[8:9] op_sel_hi:[1,1,0]
	v_pk_fma_f32 v[36:37], v[34:35], v[36:37], s[8:9] op_sel_hi:[1,1,0]
	s_mov_b32 s8, 0xffffffffbd8ff74d
	s_nop 0
	v_pk_fma_f32 v[38:39], v[14:15], v[38:39], s[8:9] op_sel_hi:[1,1,0]
	v_pk_fma_f32 v[40:41], v[18:19], v[40:41], s[8:9] op_sel_hi:[1,1,0]
	v_pk_fma_f32 v[42:43], v[30:31], v[42:43], s[8:9] op_sel_hi:[1,1,0]
	v_pk_fma_f32 v[36:37], v[34:35], v[36:37], s[8:9] op_sel_hi:[1,1,0]
	s_mov_b32 s8, 0x3e10c1ad
	s_nop 0
	v_pk_fma_f32 v[14:15], v[14:15], v[38:39], s[8:9] op_sel_hi:[1,1,0]
	v_pk_fma_f32 v[18:19], v[18:19], v[40:41], s[8:9] op_sel_hi:[1,1,0]
	v_pk_fma_f32 v[30:31], v[30:31], v[42:43], s[8:9] op_sel_hi:[1,1,0]
	v_pk_fma_f32 v[12:13], v[12:13], v[14:15], 0.5 op_sel_hi:[1,1,0]
	v_pk_fma_f32 v[14:15], v[16:17], v[18:19], 0.5 op_sel_hi:[1,1,0]
	v_pk_mul_f32 v[12:13], v[24:25], v[12:13]
	v_pk_fma_f32 v[16:17], v[28:29], v[30:31], 0.5 op_sel_hi:[1,1,0]
	v_pk_fma_f32 v[34:35], v[34:35], v[36:37], s[8:9] op_sel_hi:[1,1,0]
	v_pk_mul_f32 v[16:17], v[20:21], v[16:17]
	v_mul_f32_e32 v8, v8, v12
	v_mul_f32_e32 v9, v9, v13
	v_pk_fma_f32 v[18:19], v[32:33], v[34:35], 0.5 op_sel_hi:[1,1,0]
	v_mul_f32_e32 v12, v4, v16
	v_cvt_pk_bf16_f32 v4, v8, v9
	v_mov_b64_e32 v[8:9], s[54:55]
	v_pk_mul_f32 v[18:19], v[22:23], v[18:19]
	v_mad_i64_i32 v[8:9], s[10:11], v44, s3, v[8:9]
	v_pk_mul_f32 v[14:15], v[26:27], v[14:15]
	v_mul_f32_e32 v7, v7, v19
	v_lshl_add_u64 v[8:9], v[190:191], 1, v[8:9]
	s_mov_b64 s[10:11], -1
	v_mul_f32_e32 v10, v10, v14
	v_mul_f32_e32 v11, v11, v15
	v_mul_f32_e32 v13, v5, v17
	v_mul_f32_e32 v14, v6, v18
	v_cvt_pk_bf16_f32 v5, v10, v11
	v_cvt_pk_bf16_f32 v6, v12, v13
	v_cvt_pk_bf16_f32 v7, v14, v7
	global_store_dwordx4 v[8:9], v[4:7], off nt
	s_cbranch_vccnz .LBB0_1234
	s_andn2_b64 vcc, exec, s[52:53]
	s_cbranch_vccnz .LBB0_1233
	s_barrier
	s_branch .LBB0_1233
